# final-norm rows: 8 loads batched per row; transpose phase + layer-1 weight transposes: loads batched before LDS writes
# speedup vs baseline: 1.0219x; 1.0058x over previous
; __device__ __forceinline__ void final_norm_rows(const LArgs& a) {
;     ...
;     for (int chunk = gw; chunk < MLAT / 16; chunk += NGW) {
; #pragma unroll 2
;         for (int r = 0; r < 16; ++r) {
;             const int row = chunk * 16 + r; const float* src = (const float*)(a.ws + WS_X) + (size_t)row * DM; f32x4 v[8]; float ss = 0.f;
; #pragma unroll
;             for (int j = 0; j < 8; ++j) { v[j] = *(const f32x4*)(src + 4 * lane + 256 * j); ss += (v[j].x * v[j].x + v[j].y * v[j].y) + (v[j].z * v[j].z + v[j].w * v[j].w); }
;             const float rn = 1.f / sqrtf(wave_sum(ss) * (1.f / DM) + 1e-6f);
; #pragma unroll
;             for (int j = 0; j < 8; ++j) { const int col = 4 * lane + 256 * j; *(f32x4*)(a.out + (size_t)row * DM + col) = v[j] * rn * cs[j]; }
.LBB0_21:
	v_lshl_add_u64 v[44:45], v[74:75], 0, s[10:11]
	v_add_co_u32_e32 v40, vcc, 0xd000000, v44
	s_nop 1
	v_addc_co_u32_e32 v41, vcc, 0, v45, vcc
	v_add_co_u32_e32 v56, vcc, s60, v44
	s_nop 1
	v_addc_co_u32_e32 v57, vcc, 0, v45, vcc
	global_load_dwordx4 v[60:63], v[40:41], off
	global_load_dwordx4 v[32:35], v[40:41], off offset:1024
	global_load_dwordx4 v[36:39], v[40:41], off offset:2048
	global_load_dwordx4 v[40:43], v[40:41], off offset:3072
	global_load_dwordx4 v[44:47], v[56:57], off
	global_load_dwordx4 v[48:51], v[56:57], off offset:1024
	global_load_dwordx4 v[52:55], v[56:57], off offset:2048
	global_load_dwordx4 v[56:59], v[56:57], off offset:3072
	s_waitcnt vmcnt(7)
	v_mul_f32_e32 v100, v61, v61
	v_mul_f32_e32 v101, v63, v63
	v_fmac_f32_e32 v100, v60, v60
	v_fmac_f32_e32 v101, v62, v62
	v_add_f32_e32 v71, v100, v101
	s_waitcnt vmcnt(6)
	v_mul_f32_e32 v100, v33, v33
	v_mul_f32_e32 v101, v35, v35
	v_fmac_f32_e32 v100, v32, v32
	v_fmac_f32_e32 v101, v34, v34
	v_add_f32_e32 v100, v100, v101
	v_add_f32_e32 v71, v71, v100
	s_waitcnt vmcnt(5)
	v_mul_f32_e32 v100, v37, v37
	v_mul_f32_e32 v101, v39, v39
	v_fmac_f32_e32 v100, v36, v36
	v_fmac_f32_e32 v101, v38, v38
	v_add_f32_e32 v100, v100, v101
	v_add_f32_e32 v71, v71, v100
	s_waitcnt vmcnt(4)
	v_mul_f32_e32 v100, v41, v41
	v_mul_f32_e32 v101, v43, v43
	v_fmac_f32_e32 v100, v40, v40
	v_fmac_f32_e32 v101, v42, v42
	v_add_f32_e32 v100, v100, v101
	v_add_f32_e32 v71, v71, v100
	s_waitcnt vmcnt(3)
	v_mul_f32_e32 v100, v45, v45
	v_mul_f32_e32 v101, v47, v47
	v_fmac_f32_e32 v100, v44, v44
	v_fmac_f32_e32 v101, v46, v46
	v_add_f32_e32 v100, v100, v101
	v_add_f32_e32 v71, v71, v100
	s_waitcnt vmcnt(2)
	v_mul_f32_e32 v100, v49, v49
	v_mul_f32_e32 v101, v51, v51
	v_fmac_f32_e32 v100, v48, v48
	v_fmac_f32_e32 v101, v50, v50
	v_add_f32_e32 v100, v100, v101
	v_add_f32_e32 v71, v71, v100
	s_waitcnt vmcnt(1)
	v_mul_f32_e32 v100, v53, v53
	v_mul_f32_e32 v101, v55, v55
	v_fmac_f32_e32 v100, v52, v52
	v_fmac_f32_e32 v101, v54, v54
	v_add_f32_e32 v100, v100, v101
	v_add_f32_e32 v71, v71, v100
	s_waitcnt vmcnt(0)
	v_mul_f32_e32 v100, v57, v57
	v_mul_f32_e32 v101, v59, v59
	v_fmac_f32_e32 v100, v56, v56
	v_fmac_f32_e32 v101, v58, v58
	v_add_f32_e32 v100, v100, v101
	v_add_f32_e32 v71, v71, v100
	ds_swizzle_b32 v79, v71 offset:swizzle(SWAP,1)
	s_waitcnt lgkmcnt(0)
	v_add_f32_e32 v71, v71, v79
	ds_swizzle_b32 v79, v71 offset:swizzle(SWAP,2)
	s_waitcnt lgkmcnt(0)
	v_add_f32_e32 v71, v71, v79
	ds_swizzle_b32 v79, v71 offset:swizzle(SWAP,4)
	s_waitcnt lgkmcnt(0)
	v_add_f32_e32 v71, v71, v79
	ds_swizzle_b32 v79, v71 offset:swizzle(SWAP,8)
	s_waitcnt lgkmcnt(0)
	v_add_f32_e32 v71, v71, v79
	ds_swizzle_b32 v79, v71 offset:swizzle(SWAP,16)
	s_waitcnt lgkmcnt(0)
	v_add_f32_e32 v71, v71, v79
	s_nop 0
	v_readlane_b32 s1, v71, 32
	v_readlane_b32 s0, v71, 0
	s_nop 0
	v_mov_b32_e32 v71, s1
	v_add_f32_e32 v71, s0, v71
	v_fmamk_f32 v71, v71, 0x3a000000, v193
	v_cmp_gt_f32_e32 vcc, s61, v71
	v_mul_f32_e32 v79, 0x4f800000, v71
	s_nop 0
	v_cndmask_b32_e32 v71, v71, v79, vcc
	v_sqrt_f32_e32 v79, v71
	s_nop 0
	v_add_u32_e32 v80, -1, v79
	v_fma_f32 v83, -v80, v79, v71
	v_cmp_ge_f32_e64 s[0:1], 0, v83
	v_add_u32_e32 v83, 1, v79
	s_nop 0
	v_cndmask_b32_e64 v80, v79, v80, s[0:1]
	v_fma_f32 v79, -v83, v79, v71
	v_cmp_lt_f32_e64 s[0:1], 0, v79
	s_nop 1
	v_cndmask_b32_e64 v79, v80, v83, s[0:1]
	v_mul_f32_e32 v80, 0x37800000, v79
	v_cndmask_b32_e32 v79, v79, v80, vcc
	v_cmp_class_f32_e32 vcc, v71, v194
	s_nop 1
	v_cndmask_b32_e32 v71, v79, v71, vcc
	v_div_scale_f32 v79, s[0:1], v71, v71, 1.0
	v_rcp_f32_e32 v80, v79
	s_nop 0
	v_fma_f32 v83, -v79, v80, 1.0
	v_fmac_f32_e32 v80, v83, v80
	v_div_scale_f32 v83, vcc, 1.0, v71, 1.0
	v_mul_f32_e32 v84, v83, v80
	v_fma_f32 v85, -v79, v84, v83
	v_fmac_f32_e32 v84, v85, v80
	v_fma_f32 v79, -v79, v84, v83
	v_div_fmas_f32 v79, v79, v80, v84
	v_div_fixup_f32 v80, v79, v71, 1.0
	v_pk_mul_f32 v[32:33], v[32:33], v[80:81] op_sel_hi:[1,0]
	v_pk_mul_f32 v[34:35], v[34:35], v[80:81] op_sel_hi:[1,0]
	v_lshl_add_u64 v[84:85], v[76:77], 0, s[10:11]
	v_pk_mul_f32 v[34:35], v[6:7], v[34:35]
	v_pk_mul_f32 v[32:33], v[4:5], v[32:33]
	global_store_dwordx4 v[84:85], v[32:35], off offset:1024
	v_pk_mul_f32 v[60:61], v[60:61], v[80:81] op_sel_hi:[1,0]
	v_pk_mul_f32 v[62:63], v[62:63], v[80:81] op_sel_hi:[1,0]
	v_pk_mul_f32 v[32:33], v[36:37], v[80:81] op_sel_hi:[1,0]
	v_pk_mul_f32 v[34:35], v[38:39], v[80:81] op_sel_hi:[1,0]
	v_pk_mul_f32 v[32:33], v[8:9], v[32:33]
	v_pk_mul_f32 v[34:35], v[10:11], v[34:35]
	global_store_dwordx4 v[84:85], v[32:35], off offset:2048
	v_add_co_u32_e32 v36, vcc, s40, v84
	s_nop 0
	v_pk_mul_f32 v[32:33], v[40:41], v[80:81] op_sel_hi:[1,0]
	v_pk_mul_f32 v[34:35], v[42:43], v[80:81] op_sel_hi:[1,0]
	v_pk_mul_f32 v[32:33], v[12:13], v[32:33]
	v_pk_mul_f32 v[34:35], v[14:15], v[34:35]
	global_store_dwordx4 v[84:85], v[32:35], off offset:3072
	v_addc_co_u32_e32 v37, vcc, 0, v85, vcc
	s_nop 0
	v_pk_mul_f32 v[32:33], v[44:45], v[80:81] op_sel_hi:[1,0]
	v_pk_mul_f32 v[34:35], v[46:47], v[80:81] op_sel_hi:[1,0]
	v_pk_mul_f32 v[32:33], v[16:17], v[32:33]
	v_pk_mul_f32 v[34:35], v[18:19], v[34:35]
	global_store_dwordx4 v[36:37], v[32:35], off
	v_pk_mul_f32 v[62:63], v[2:3], v[62:63]
	v_pk_mul_f32 v[60:61], v[0:1], v[60:61]
	v_pk_mul_f32 v[32:33], v[48:49], v[80:81] op_sel_hi:[1,0]
	v_pk_mul_f32 v[34:35], v[50:51], v[80:81] op_sel_hi:[1,0]
	v_pk_mul_f32 v[32:33], v[20:21], v[32:33]
	v_pk_mul_f32 v[34:35], v[22:23], v[34:35]
	global_store_dwordx4 v[36:37], v[32:35], off offset:1024
	v_ashrrev_i32_e32 v79, 31, v78
	global_store_dwordx4 v[84:85], v[60:63], off
	v_pk_mul_f32 v[32:33], v[52:53], v[80:81] op_sel_hi:[1,0]
	v_pk_mul_f32 v[34:35], v[54:55], v[80:81] op_sel_hi:[1,0]
	v_pk_mul_f32 v[32:33], v[24:25], v[32:33]
	v_pk_mul_f32 v[34:35], v[26:27], v[34:35]
	global_store_dwordx4 v[36:37], v[32:35], off offset:2048
	v_lshlrev_b64 v[84:85], 13, v[78:79]
	v_lshl_add_u64 v[48:49], v[64:65], 0, v[84:85]
	v_pk_mul_f32 v[32:33], v[56:57], v[80:81] op_sel_hi:[1,0]
	v_pk_mul_f32 v[34:35], v[58:59], v[80:81] op_sel_hi:[1,0]
	v_pk_mul_f32 v[32:33], v[28:29], v[32:33]
	v_pk_mul_f32 v[34:35], v[30:31], v[34:35]
	global_store_dwordx4 v[36:37], v[32:35], off offset:3072
	v_add_co_u32_e32 v60, vcc, s40, v48
	v_lshl_add_u64 v[84:85], v[66:67], 0, v[84:85]
	s_nop 0
	v_addc_co_u32_e32 v61, vcc, 0, v49, vcc
	s_add_u32 s10, s10, 0x4000
	s_addc_u32 s11, s11, 0
	v_add_u32_e32 v78, 2, v78
	global_load_dwordx4 v[32:35], v[48:49], off
	global_load_dwordx4 v[36:39], v[48:49], off offset:1024
	global_load_dwordx4 v[40:43], v[48:49], off offset:2048
	global_load_dwordx4 v[44:47], v[48:49], off offset:3072
	global_load_dwordx4 v[48:51], v[60:61], off
	global_load_dwordx4 v[52:55], v[60:61], off offset:1024
	global_load_dwordx4 v[56:59], v[60:61], off offset:2048
	global_load_dwordx4 v[60:63], v[60:61], off offset:3072
	s_cmp_eq_u32 s10, 0x20000
	s_waitcnt vmcnt(7)
; __device__ __forceinline__ void final_norm_rows(const LArgs& a) {
;     ...
;     for (int chunk = gw; chunk < MLAT / 16; chunk += NGW) {
; #pragma unroll 2
;         for (int r = 0; r < 16; ++r) {
;             const int row = chunk * 16 + r; const float* src = (const float*)(a.ws + WS_X) + (size_t)row * DM; f32x4 v[8]; float ss = 0.f;
; #pragma unroll
;             for (int j = 0; j < 8; ++j) { v[j] = *(const f32x4*)(src + 4 * lane + 256 * j); ss += (v[j].x * v[j].x + v[j].y * v[j].y) + (v[j].z * v[j].z + v[j].w * v[j].w); }
;             const float rn = 1.f / sqrtf(wave_sum(ss) * (1.f / DM) + 1e-6f);
; #pragma unroll
;             for (int j = 0; j < 8; ++j) { const int col = 4 * lane + 256 * j; *(f32x4*)(a.out + (size_t)row * DM + col) = v[j] * rn * cs[j]; }
	v_mul_f32_e32 v100, v33, v33
	v_mul_f32_e32 v101, v35, v35
	v_fmac_f32_e32 v100, v32, v32
	v_fmac_f32_e32 v101, v34, v34
	v_add_f32_e32 v71, v100, v101
	s_waitcnt vmcnt(6)
	v_mul_f32_e32 v100, v37, v37
	v_mul_f32_e32 v101, v39, v39
	v_fmac_f32_e32 v100, v36, v36
	v_fmac_f32_e32 v101, v38, v38
	v_add_f32_e32 v100, v100, v101
	v_add_f32_e32 v71, v71, v100
	s_waitcnt vmcnt(5)
	v_mul_f32_e32 v100, v41, v41
	v_mul_f32_e32 v101, v43, v43
	v_fmac_f32_e32 v100, v40, v40
	v_fmac_f32_e32 v101, v42, v42
	v_add_f32_e32 v100, v100, v101
	v_add_f32_e32 v71, v71, v100
	s_waitcnt vmcnt(4)
	v_mul_f32_e32 v100, v45, v45
	v_mul_f32_e32 v101, v47, v47
	v_fmac_f32_e32 v100, v44, v44
	v_fmac_f32_e32 v101, v46, v46
	v_add_f32_e32 v100, v100, v101
	v_add_f32_e32 v71, v71, v100
	s_waitcnt vmcnt(3)
	v_mul_f32_e32 v100, v49, v49
	v_mul_f32_e32 v101, v51, v51
	v_fmac_f32_e32 v100, v48, v48
	v_fmac_f32_e32 v101, v50, v50
	v_add_f32_e32 v100, v100, v101
	v_add_f32_e32 v71, v71, v100
	s_waitcnt vmcnt(2)
	v_mul_f32_e32 v100, v53, v53
	v_mul_f32_e32 v101, v55, v55
	v_fmac_f32_e32 v100, v52, v52
	v_fmac_f32_e32 v101, v54, v54
	v_add_f32_e32 v100, v100, v101
	v_add_f32_e32 v71, v71, v100
	s_waitcnt vmcnt(1)
	v_mul_f32_e32 v100, v57, v57
	v_mul_f32_e32 v101, v59, v59
	v_fmac_f32_e32 v100, v56, v56
	v_fmac_f32_e32 v101, v58, v58
	v_add_f32_e32 v100, v100, v101
	v_add_f32_e32 v71, v71, v100
	s_waitcnt vmcnt(0)
	v_mul_f32_e32 v100, v61, v61
	v_mul_f32_e32 v101, v63, v63
	v_fmac_f32_e32 v100, v60, v60
	v_fmac_f32_e32 v101, v62, v62
	v_add_f32_e32 v100, v100, v101
	v_add_f32_e32 v71, v71, v100
	ds_swizzle_b32 v79, v71 offset:swizzle(SWAP,1)
	s_waitcnt lgkmcnt(0)
	v_add_f32_e32 v71, v71, v79
	ds_swizzle_b32 v79, v71 offset:swizzle(SWAP,2)
	s_waitcnt lgkmcnt(0)
	v_add_f32_e32 v71, v71, v79
	ds_swizzle_b32 v79, v71 offset:swizzle(SWAP,4)
	s_waitcnt lgkmcnt(0)
	v_add_f32_e32 v71, v71, v79
	ds_swizzle_b32 v79, v71 offset:swizzle(SWAP,8)
	s_waitcnt lgkmcnt(0)
	v_add_f32_e32 v71, v71, v79
	ds_swizzle_b32 v79, v71 offset:swizzle(SWAP,16)
	s_waitcnt lgkmcnt(0)
	v_add_f32_e32 v71, v71, v79
	s_nop 0
	v_readlane_b32 s1, v71, 32
	v_readlane_b32 s0, v71, 0
	s_nop 0
	v_mov_b32_e32 v71, s1
	v_add_f32_e32 v71, s0, v71
	v_fmamk_f32 v71, v71, 0x3a000000, v193
	v_cmp_gt_f32_e32 vcc, s61, v71
	v_mul_f32_e32 v79, 0x4f800000, v71
	s_nop 0
	v_cndmask_b32_e32 v71, v71, v79, vcc
	v_sqrt_f32_e32 v79, v71
	s_nop 0
	v_add_u32_e32 v80, -1, v79
	v_fma_f32 v83, -v80, v79, v71
	v_cmp_ge_f32_e64 s[0:1], 0, v83
	v_add_u32_e32 v83, 1, v79
	s_nop 0
	v_cndmask_b32_e64 v80, v79, v80, s[0:1]
	v_fma_f32 v79, -v83, v79, v71
	v_cmp_lt_f32_e64 s[0:1], 0, v79
	s_nop 1
	v_cndmask_b32_e64 v79, v80, v83, s[0:1]
	v_mul_f32_e32 v80, 0x37800000, v79
	v_cndmask_b32_e32 v79, v79, v80, vcc
	v_cmp_class_f32_e32 vcc, v71, v194
	s_nop 1
	v_cndmask_b32_e32 v71, v79, v71, vcc
	v_div_scale_f32 v79, s[0:1], v71, v71, 1.0
	v_rcp_f32_e32 v80, v79
	s_nop 0
	v_fma_f32 v83, -v79, v80, 1.0
	v_fmac_f32_e32 v80, v83, v80
	v_div_scale_f32 v83, vcc, 1.0, v71, 1.0
	v_mul_f32_e32 v86, v83, v80
	v_fma_f32 v87, -v79, v86, v83
	v_fmac_f32_e32 v86, v87, v80
	v_fma_f32 v79, -v79, v86, v83
	v_div_fmas_f32 v79, v79, v80, v86
	v_div_fixup_f32 v80, v79, v71, 1.0
	v_pk_mul_f32 v[32:33], v[32:33], v[80:81] op_sel_hi:[1,0]
	v_pk_mul_f32 v[34:35], v[34:35], v[80:81] op_sel_hi:[1,0]
	v_pk_mul_f32 v[32:33], v[0:1], v[32:33]
	v_pk_mul_f32 v[34:35], v[2:3], v[34:35]
	global_store_dwordx4 v[84:85], v[32:35], off
	s_nop 1
	v_pk_mul_f32 v[32:33], v[36:37], v[80:81] op_sel_hi:[1,0]
	v_pk_mul_f32 v[34:35], v[38:39], v[80:81] op_sel_hi:[1,0]
	v_pk_mul_f32 v[32:33], v[4:5], v[32:33]
	v_pk_mul_f32 v[34:35], v[6:7], v[34:35]
	global_store_dwordx4 v[84:85], v[32:35], off offset:1024
	v_add_co_u32_e32 v36, vcc, s40, v84
	s_nop 0
	v_pk_mul_f32 v[32:33], v[40:41], v[80:81] op_sel_hi:[1,0]
	v_pk_mul_f32 v[34:35], v[42:43], v[80:81] op_sel_hi:[1,0]
	v_pk_mul_f32 v[32:33], v[8:9], v[32:33]
	v_pk_mul_f32 v[34:35], v[10:11], v[34:35]
	global_store_dwordx4 v[84:85], v[32:35], off offset:2048
	v_addc_co_u32_e32 v37, vcc, 0, v85, vcc
	s_nop 0
	v_pk_mul_f32 v[32:33], v[44:45], v[80:81] op_sel_hi:[1,0]
	v_pk_mul_f32 v[34:35], v[46:47], v[80:81] op_sel_hi:[1,0]
	v_pk_mul_f32 v[32:33], v[12:13], v[32:33]
	v_pk_mul_f32 v[34:35], v[14:15], v[34:35]
	global_store_dwordx4 v[84:85], v[32:35], off offset:3072
	s_nop 1
	v_pk_mul_f32 v[32:33], v[48:49], v[80:81] op_sel_hi:[1,0]
	v_pk_mul_f32 v[34:35], v[50:51], v[80:81] op_sel_hi:[1,0]
	v_pk_mul_f32 v[32:33], v[16:17], v[32:33]
	v_pk_mul_f32 v[34:35], v[18:19], v[34:35]
	global_store_dwordx4 v[36:37], v[32:35], off
	s_nop 1
	v_pk_mul_f32 v[32:33], v[52:53], v[80:81] op_sel_hi:[1,0]
	v_pk_mul_f32 v[34:35], v[54:55], v[80:81] op_sel_hi:[1,0]
	v_pk_mul_f32 v[32:33], v[20:21], v[32:33]
	v_pk_mul_f32 v[34:35], v[22:23], v[34:35]
	global_store_dwordx4 v[36:37], v[32:35], off offset:1024
	s_nop 1
	v_pk_mul_f32 v[32:33], v[56:57], v[80:81] op_sel_hi:[1,0]
	v_pk_mul_f32 v[34:35], v[58:59], v[80:81] op_sel_hi:[1,0]
	v_pk_mul_f32 v[32:33], v[24:25], v[32:33]
	v_pk_mul_f32 v[34:35], v[26:27], v[34:35]
	global_store_dwordx4 v[36:37], v[32:35], off offset:2048
	s_nop 1
	v_pk_mul_f32 v[32:33], v[60:61], v[80:81] op_sel_hi:[1,0]
	v_pk_mul_f32 v[34:35], v[62:63], v[80:81] op_sel_hi:[1,0]
	v_pk_mul_f32 v[32:33], v[28:29], v[32:33]
	v_pk_mul_f32 v[34:35], v[30:31], v[34:35]
	global_store_dwordx4 v[36:37], v[32:35], off offset:3072
	s_cbranch_scc0 .LBB0_21
	v_add_u32_e32 v81, s86, v81
	v_readlane_b32 s0, v254, 6
	v_cmp_lt_i32_e32 vcc, s82, v81
	s_or_b64 s[8:9], vcc, s[8:9]
	v_add_u32_e32 v82, s0, v82
	v_add_u32_e32 v70, s0, v70
	s_andn2_b64 exec, exec, s[8:9]
	s_cbranch_execnz .LBB0_20

; #define LAS __attribute__((address_space(3)))
; __device__ __forceinline__ void transpose_phase(const LArgs& a, LAS unsigned char* lds) {
;     ...
;     for (int it = gw; it < 32 * 512; it += NGW) {
;         const int c0 = (it & 31) * 64, t0 = (it >> 5) * 64;
; #pragma unroll
;         for (int i = 0; i < 8; ++i) { const int ch = 8 * i + (lane >> 3), k = lane & 7; *(LAS u32x4*)(T + ch * 72 + 8 * k) = *(const u32x4*)(YT + (size_t)(c0 + ch) * MLAT + t0 + 8 * k); }
;         asm volatile("s_waitcnt vmcnt(0) lgkmcnt(0)" ::: "memory");
; #pragma unroll
;         for (int i = 0; i < 8; ++i) { const int t = 8 * i + (lane >> 3), k = lane & 7; unsigned short e[8];
; #pragma unroll
;             for (int q = 0; q < 8; ++q) e[q] = T[(8 * k + q) * 72 + t];
;             u32x4 w; w.x = e[0] | ((unsigned)e[1] << 16); w.y = e[2] | ((unsigned)e[3] << 16); w.z = e[4] | ((unsigned)e[5] << 16); w.w = e[6] | ((unsigned)e[7] << 16);
;             *(u32x4*)(Y + (size_t)(t0 + t) * DM + c0 + 8 * k) = w; }
.LBB0_35:
	v_and_b32_e32 v22, 0xffffffc0, v14
	v_and_b32_e32 v17, 0x7c0, v15
	v_ashrrev_i32_e32 v23, 31, v22
	v_lshl_add_u64 v[24:25], v[22:23], 1, v[0:1]
	v_or_b32_sdwa v172, v17, v5 dst_sel:WORD_1 dst_unused:UNUSED_PAD src0_sel:DWORD src1_sel:DWORD
	v_add_u32_e32 v4, s86, v4
	v_lshl_add_u64 v[28:29], v[24:25], 0, v[172:173]
	v_or_b32_sdwa v172, v17, v8 dst_sel:WORD_1 dst_unused:UNUSED_PAD src0_sel:DWORD src1_sel:DWORD
	global_load_dwordx4 v[100:103], v[28:29], off
	v_lshl_add_u64 v[30:31], v[24:25], 0, v[172:173]
	v_or_b32_sdwa v172, v17, v9 dst_sel:WORD_1 dst_unused:UNUSED_PAD src0_sel:DWORD src1_sel:DWORD
	global_load_dwordx4 v[104:107], v[30:31], off
	v_lshl_add_u64 v[28:29], v[24:25], 0, v[172:173]
	v_or_b32_sdwa v172, v17, v10 dst_sel:WORD_1 dst_unused:UNUSED_PAD src0_sel:DWORD src1_sel:DWORD
	global_load_dwordx4 v[108:111], v[28:29], off
	v_lshl_add_u64 v[30:31], v[24:25], 0, v[172:173]
	v_or_b32_sdwa v172, v17, v11 dst_sel:WORD_1 dst_unused:UNUSED_PAD src0_sel:DWORD src1_sel:DWORD
	global_load_dwordx4 v[112:115], v[30:31], off
	v_lshl_add_u64 v[28:29], v[24:25], 0, v[172:173]
	v_or_b32_sdwa v172, v17, v12 dst_sel:WORD_1 dst_unused:UNUSED_PAD src0_sel:DWORD src1_sel:DWORD
	global_load_dwordx4 v[116:119], v[28:29], off
	v_lshl_add_u64 v[30:31], v[24:25], 0, v[172:173]
	v_or_b32_sdwa v172, v17, v13 dst_sel:WORD_1 dst_unused:UNUSED_PAD src0_sel:DWORD src1_sel:DWORD
	global_load_dwordx4 v[120:123], v[30:31], off
	v_lshl_add_u64 v[28:29], v[24:25], 0, v[172:173]
	v_or_b32_sdwa v172, v17, v6 dst_sel:WORD_1 dst_unused:UNUSED_PAD src0_sel:DWORD src1_sel:DWORD
	global_load_dwordx4 v[124:127], v[28:29], off
	v_lshl_add_u64 v[30:31], v[24:25], 0, v[172:173]
	v_cmp_lt_i32_e32 vcc, s42, v4
	global_load_dwordx4 v[128:131], v[30:31], off
	v_add_u32_e32 v14, s91, v14
	v_add_u32_e32 v15, s90, v15
	s_or_b64 s[6:7], vcc, s[6:7]
	v_lshlrev_b32_e32 v172, 1, v17
	v_lshl_add_u64 v[24:25], v[2:3], 0, v[172:173]
	s_waitcnt vmcnt(7)
	ds_write_b128 v16, v[100:103]
	s_waitcnt vmcnt(6)
	ds_write_b128 v16, v[104:107] offset:1152
	s_waitcnt vmcnt(5)
	ds_write_b128 v16, v[108:111] offset:2304
	s_waitcnt vmcnt(4)
	ds_write_b128 v16, v[112:115] offset:3456
	s_waitcnt vmcnt(3)
	ds_write_b128 v16, v[116:119] offset:4608
	s_waitcnt vmcnt(2)
	ds_write_b128 v16, v[120:123] offset:5760
	s_waitcnt vmcnt(1)
	ds_write_b128 v16, v[124:127] offset:6912
	s_waitcnt vmcnt(0)
	ds_write_b128 v16, v[128:131] offset:8064
	s_waitcnt vmcnt(0) lgkmcnt(0)
	ds_read_u16 v17, v7 offset:144
	ds_read_u16 v18, v7 offset:288
	ds_read_u16 v19, v7 offset:432
	ds_read_u16 v20, v7 offset:576
	ds_read_u16 v23, v7 offset:720
	ds_read_u16 v21, v7 offset:864
	ds_read_u16 v26, v7 offset:1008
	s_waitcnt lgkmcnt(4)
	v_perm_b32 v19, v19, v18, s41
	s_waitcnt lgkmcnt(2)
	v_perm_b32 v20, v23, v20, s41
	ds_read_u16 v18, v7
	ds_read_u16 v23, v7 offset:16
	s_waitcnt lgkmcnt(2)
	v_perm_b32 v21, v26, v21, s41
	v_or_b32_e32 v26, v22, v5
	v_ashrrev_i32_e32 v27, 31, v26
	v_lshlrev_b64 v[26:27], 12, v[26:27]
	s_waitcnt lgkmcnt(1)
	v_perm_b32 v18, v17, v18, s41
	v_lshl_add_u64 v[26:27], v[24:25], 0, v[26:27]
	global_store_dwordx4 v[26:27], v[18:21], off
	ds_read_u16 v17, v7 offset:160
	ds_read_u16 v18, v7 offset:304
	ds_read_u16 v19, v7 offset:448
	ds_read_u16 v20, v7 offset:592
	ds_read_u16 v26, v7 offset:736
	ds_read_u16 v21, v7 offset:880
	ds_read_u16 v27, v7 offset:1024
	s_waitcnt lgkmcnt(4)
	v_perm_b32 v19, v19, v18, s41
	v_perm_b32 v18, v17, v23, s41
	s_waitcnt lgkmcnt(2)
	v_perm_b32 v20, v26, v20, s41
	v_or_b32_e32 v26, v22, v8
	s_waitcnt lgkmcnt(0)
	v_perm_b32 v21, v27, v21, s41
	v_ashrrev_i32_e32 v27, 31, v26
	v_lshlrev_b64 v[26:27], 12, v[26:27]
	v_lshl_add_u64 v[26:27], v[24:25], 0, v[26:27]
	global_store_dwordx4 v[26:27], v[18:21], off
	ds_read_u16 v17, v7 offset:176
	ds_read_u16 v18, v7 offset:320
	ds_read_u16 v19, v7 offset:464
	ds_read_u16 v20, v7 offset:608
	ds_read_u16 v23, v7 offset:752
	ds_read_u16 v21, v7 offset:896
	ds_read_u16 v26, v7 offset:1040
	s_waitcnt lgkmcnt(4)
; __device__ __forceinline__ void transpose_phase(const LArgs& a, LAS unsigned char* lds) {
;     ...
;         for (int i = 0; i < 8; ++i) { const int t = 8 * i + (lane >> 3), k = lane & 7; unsigned short e[8];
; #pragma unroll
;             for (int q = 0; q < 8; ++q) e[q] = T[(8 * k + q) * 72 + t];
;             u32x4 w; w.x = e[0] | ((unsigned)e[1] << 16); w.y = e[2] | ((unsigned)e[3] << 16); w.z = e[4] | ((unsigned)e[5] << 16); w.w = e[6] | ((unsigned)e[7] << 16);
;             *(u32x4*)(Y + (size_t)(t0 + t) * DM + c0 + 8 * k) = w; }
;         asm volatile("s_waitcnt lgkmcnt(0)" ::: "memory");
;     }
	v_perm_b32 v19, v19, v18, s41
	s_waitcnt lgkmcnt(2)
	v_perm_b32 v20, v23, v20, s41
	ds_read_u16 v18, v7 offset:32
	ds_read_u16 v23, v7 offset:48
	s_waitcnt lgkmcnt(2)
	v_perm_b32 v21, v26, v21, s41
	v_or_b32_e32 v26, v22, v9
	v_ashrrev_i32_e32 v27, 31, v26
	v_lshlrev_b64 v[26:27], 12, v[26:27]
	s_waitcnt lgkmcnt(1)
	v_perm_b32 v18, v17, v18, s41
	v_lshl_add_u64 v[26:27], v[24:25], 0, v[26:27]
	global_store_dwordx4 v[26:27], v[18:21], off
	ds_read_u16 v17, v7 offset:192
	ds_read_u16 v18, v7 offset:336
	ds_read_u16 v19, v7 offset:480
	ds_read_u16 v20, v7 offset:624
	ds_read_u16 v26, v7 offset:768
	ds_read_u16 v21, v7 offset:912
	ds_read_u16 v27, v7 offset:1056
	s_waitcnt lgkmcnt(4)
	v_perm_b32 v19, v19, v18, s41
	v_perm_b32 v18, v17, v23, s41
	s_waitcnt lgkmcnt(2)
	v_perm_b32 v20, v26, v20, s41
	v_or_b32_e32 v26, v22, v10
	s_waitcnt lgkmcnt(0)
	v_perm_b32 v21, v27, v21, s41
	v_ashrrev_i32_e32 v27, 31, v26
	v_lshlrev_b64 v[26:27], 12, v[26:27]
	v_lshl_add_u64 v[26:27], v[24:25], 0, v[26:27]
	global_store_dwordx4 v[26:27], v[18:21], off
	ds_read_u16 v17, v7 offset:64
	ds_read_u16 v18, v7 offset:208
	ds_read_u16 v19, v7 offset:352
	ds_read_u16 v23, v7 offset:496
	ds_read_u16 v20, v7 offset:640
	ds_read_u16 v26, v7 offset:784
	ds_read_u16 v21, v7 offset:928
	ds_read_u16 v27, v7 offset:1072
	s_waitcnt lgkmcnt(4)
	v_perm_b32 v19, v23, v19, s41
	v_perm_b32 v18, v18, v17, s41
	s_waitcnt lgkmcnt(2)
	v_perm_b32 v20, v26, v20, s41
	v_or_b32_e32 v26, v22, v11
	s_waitcnt lgkmcnt(0)
	v_perm_b32 v21, v27, v21, s41
	v_ashrrev_i32_e32 v27, 31, v26
	v_lshlrev_b64 v[26:27], 12, v[26:27]
	v_lshl_add_u64 v[26:27], v[24:25], 0, v[26:27]
	global_store_dwordx4 v[26:27], v[18:21], off
	ds_read_u16 v17, v7 offset:80
	ds_read_u16 v18, v7 offset:224
	ds_read_u16 v19, v7 offset:368
	ds_read_u16 v23, v7 offset:512
	ds_read_u16 v20, v7 offset:656
	ds_read_u16 v26, v7 offset:800
	ds_read_u16 v21, v7 offset:944
	ds_read_u16 v27, v7 offset:1088
	s_waitcnt lgkmcnt(4)
	v_perm_b32 v19, v23, v19, s41
	v_perm_b32 v18, v18, v17, s41
	s_waitcnt lgkmcnt(2)
	v_perm_b32 v20, v26, v20, s41
	v_or_b32_e32 v26, v22, v12
	s_waitcnt lgkmcnt(0)
	v_perm_b32 v21, v27, v21, s41
	v_ashrrev_i32_e32 v27, 31, v26
	v_lshlrev_b64 v[26:27], 12, v[26:27]
	v_lshl_add_u64 v[26:27], v[24:25], 0, v[26:27]
	global_store_dwordx4 v[26:27], v[18:21], off
	ds_read_u16 v17, v7 offset:96
	ds_read_u16 v18, v7 offset:240
	ds_read_u16 v19, v7 offset:384
	ds_read_u16 v23, v7 offset:528
	ds_read_u16 v20, v7 offset:672
	ds_read_u16 v26, v7 offset:816
	ds_read_u16 v21, v7 offset:960
	ds_read_u16 v27, v7 offset:1104
	s_waitcnt lgkmcnt(4)
	v_perm_b32 v19, v23, v19, s41
	v_perm_b32 v18, v18, v17, s41
	s_waitcnt lgkmcnt(2)
	v_perm_b32 v20, v26, v20, s41
	v_or_b32_e32 v26, v22, v13
	s_waitcnt lgkmcnt(0)
	v_perm_b32 v21, v27, v21, s41
	v_ashrrev_i32_e32 v27, 31, v26
	v_lshlrev_b64 v[26:27], 12, v[26:27]
	v_lshl_add_u64 v[26:27], v[24:25], 0, v[26:27]
	global_store_dwordx4 v[26:27], v[18:21], off
	ds_read_u16 v17, v7 offset:112
	ds_read_u16 v18, v7 offset:256
	ds_read_u16 v19, v7 offset:400
	ds_read_u16 v23, v7 offset:544
	ds_read_u16 v20, v7 offset:688
	ds_read_u16 v26, v7 offset:832
	ds_read_u16 v21, v7 offset:976
	ds_read_u16 v27, v7 offset:1120
	v_or_b32_e32 v22, v22, v6
	s_waitcnt lgkmcnt(4)
	v_perm_b32 v19, v23, v19, s41
	v_ashrrev_i32_e32 v23, 31, v22
	v_lshlrev_b64 v[22:23], 12, v[22:23]
	s_waitcnt lgkmcnt(0)
	v_perm_b32 v21, v27, v21, s41
	v_perm_b32 v20, v26, v20, s41
	v_perm_b32 v18, v18, v17, s41
	v_lshl_add_u64 v[22:23], v[24:25], 0, v[22:23]
	global_store_dwordx4 v[22:23], v[18:21], off
	s_waitcnt lgkmcnt(0)
	s_andn2_b64 exec, exec, s[6:7]
	s_cbranch_execnz .LBB0_35

; __device__ __forceinline__ void transpose_item(const float* W, int K, int N, bf16* WT, int dst_row0, LAS float* scr, int k0, int n0, int lane) {
; #pragma unroll 8
;     for (int i = 0; i < 32; ++i) { const int kk = 2 * i + (lane >> 5); scr[kk * 33 + (lane & 31)] = W[(size_t)(k0 + kk) * N + n0 + (lane & 31)]; }
;     asm volatile("s_waitcnt vmcnt(0) lgkmcnt(0)" ::: "memory");
.LBB0_372:
	s_lshl_b32 s8, s3, 1
	s_lshl_b32 s7, s2, 1
	v_or_b32_e32 v11, s8, v0
	v_or_b32_e32 v9, s7, v1
	v_add_u32_e32 v24, v11, v10
	v_add_u32_e32 v26, v9, v5
	v_mad_i64_i32 v[24:25], s[10:11], v24, s53, v[12:13]
	v_mad_i64_i32 v[26:27], s[10:11], v26, s53, v[12:13]
	global_load_dword v100, v[24:25], off
	global_load_dword v101, v[26:27], off
	v_mad_u64_u32 v[120:121], s[10:11], v11, s55, v[4:5]
	v_mad_u64_u32 v[122:123], s[10:11], v9, s55, v[4:5]
	s_add_i32 s10, s8, 4
	s_add_i32 s9, s7, 4
	v_or_b32_e32 v11, s10, v0
	v_or_b32_e32 v9, s9, v1
	s_add_i32 s9, s7, 8
	s_add_i32 s3, s3, 16
	s_add_i32 s2, s2, 16
	s_add_i32 s6, s6, -16
	v_add_u32_e32 v24, v11, v10
	v_add_u32_e32 v26, v9, v5
	v_mad_i64_i32 v[24:25], s[10:11], v24, s53, v[12:13]
	v_mad_i64_i32 v[26:27], s[10:11], v26, s53, v[12:13]
	global_load_dword v102, v[24:25], off
	global_load_dword v103, v[26:27], off
	v_mad_u64_u32 v[124:125], s[10:11], v11, s55, v[4:5]
	v_mad_u64_u32 v[126:127], s[10:11], v9, s55, v[4:5]
	s_add_i32 s10, s8, 8
	s_nop 0
	v_or_b32_e32 v11, s10, v0
	v_or_b32_e32 v9, s9, v1
	s_add_i32 s9, s7, 12
	v_add_u32_e32 v24, v11, v10
	v_add_u32_e32 v26, v9, v5
	v_mad_i64_i32 v[24:25], s[10:11], v24, s53, v[12:13]
	v_mad_i64_i32 v[26:27], s[10:11], v26, s53, v[12:13]
	global_load_dword v104, v[24:25], off
	global_load_dword v105, v[26:27], off
	v_mad_u64_u32 v[128:129], s[10:11], v11, s55, v[4:5]
	v_mad_u64_u32 v[130:131], s[10:11], v9, s55, v[4:5]
	s_add_i32 s10, s8, 12
	s_nop 0
	v_or_b32_e32 v11, s10, v0
	v_or_b32_e32 v9, s9, v1
	s_add_i32 s9, s7, 16
	v_add_u32_e32 v24, v11, v10
	v_add_u32_e32 v26, v9, v5
	v_mad_i64_i32 v[24:25], s[10:11], v24, s53, v[12:13]
	v_mad_i64_i32 v[26:27], s[10:11], v26, s53, v[12:13]
	global_load_dword v106, v[24:25], off
	global_load_dword v107, v[26:27], off
	v_mad_u64_u32 v[132:133], s[10:11], v11, s55, v[4:5]
	v_mad_u64_u32 v[134:135], s[10:11], v9, s55, v[4:5]
	s_add_i32 s10, s8, 16
	s_nop 0
	v_or_b32_e32 v11, s10, v0
	v_or_b32_e32 v9, s9, v1
	s_add_i32 s9, s7, 20
	v_add_u32_e32 v24, v11, v10
	v_add_u32_e32 v26, v9, v5
	v_mad_i64_i32 v[24:25], s[10:11], v24, s53, v[12:13]
	v_mad_i64_i32 v[26:27], s[10:11], v26, s53, v[12:13]
	global_load_dword v108, v[24:25], off
	global_load_dword v109, v[26:27], off
	v_mad_u64_u32 v[136:137], s[10:11], v11, s55, v[4:5]
	v_mad_u64_u32 v[138:139], s[10:11], v9, s55, v[4:5]
	s_add_i32 s10, s8, 20
	s_nop 0
	v_or_b32_e32 v11, s10, v0
	v_or_b32_e32 v9, s9, v1
	s_add_i32 s9, s7, 24
	s_add_i32 s7, s7, 28
	v_add_u32_e32 v24, v11, v10
	v_add_u32_e32 v26, v9, v5
	v_mad_i64_i32 v[24:25], s[10:11], v24, s53, v[12:13]
	v_mad_i64_i32 v[26:27], s[10:11], v26, s53, v[12:13]
	global_load_dword v110, v[24:25], off
	global_load_dword v111, v[26:27], off
	v_mad_u64_u32 v[140:141], s[10:11], v11, s55, v[4:5]
	v_mad_u64_u32 v[142:143], s[10:11], v9, s55, v[4:5]
	s_add_i32 s10, s8, 24
	s_nop 0
	v_or_b32_e32 v11, s10, v0
	v_or_b32_e32 v9, s9, v1
	s_add_i32 s8, s8, 28
	s_cmp_lg_u32 s6, 0
	v_add_u32_e32 v24, v11, v10
	v_add_u32_e32 v26, v9, v5
	v_mad_i64_i32 v[24:25], s[10:11], v24, s53, v[12:13]
	v_mad_i64_i32 v[26:27], s[10:11], v26, s53, v[12:13]
	global_load_dword v112, v[24:25], off
	global_load_dword v113, v[26:27], off
	v_mad_u64_u32 v[144:145], s[10:11], v11, s55, v[4:5]
	v_or_b32_e32 v11, s8, v0
	v_mad_u64_u32 v[146:147], s[10:11], v9, s55, v[4:5]
	v_or_b32_e32 v9, s7, v1
	v_add_u32_e32 v24, v11, v10
	v_add_u32_e32 v26, v9, v5
	v_mad_i64_i32 v[24:25], s[8:9], v24, s53, v[12:13]
	v_mad_i64_i32 v[26:27], s[8:9], v26, s53, v[12:13]
	global_load_dword v114, v[24:25], off
	global_load_dword v115, v[26:27], off
	v_mad_u64_u32 v[148:149], s[8:9], v11, s55, v[4:5]
	v_mad_u64_u32 v[150:151], s[8:9], v9, s55, v[4:5]
	s_waitcnt vmcnt(0)
	ds_write_b32 v120, v100
	ds_write_b32 v122, v101
	ds_write_b32 v124, v102
	ds_write_b32 v126, v103
	ds_write_b32 v128, v104
	ds_write_b32 v130, v105
	ds_write_b32 v132, v106
	ds_write_b32 v134, v107
	ds_write_b32 v136, v108
	ds_write_b32 v138, v109
	ds_write_b32 v140, v110
	ds_write_b32 v142, v111
	ds_write_b32 v144, v112
	ds_write_b32 v146, v113
	ds_write_b32 v148, v114
	ds_write_b32 v150, v115
	s_cbranch_scc1 .LBB0_372
; #define LAS __attribute__((address_space(3)))
; __device__ __forceinline__ unsigned pk2(float lo, float hi) { return f2bf(lo) | (f2bf(hi) << 16); }
; __device__ __forceinline__ void transpose_item(const float* W, int K, int N, bf16* WT, int dst_row0, LAS float* scr, int k0, int n0, int lane) {
;     ...
;     const int c = lane & 7;
; #pragma unroll
;     for (int j = 0; j < 4; ++j) { const int n = (lane >> 3) + 8 * j; const LAS float* s = scr + (8 * c) * 33 + n;
;         u32x4 o; o.x = pk2(s[0 * 33], s[1 * 33]); o.y = pk2(s[2 * 33], s[3 * 33]); o.z = pk2(s[4 * 33], s[5 * 33]); o.w = pk2(s[6 * 33], s[7 * 33]);
;         *(u32x4*)(WT + (size_t)(dst_row0 + n) * K + k0 + 8 * c) = o; }
;     asm volatile("s_waitcnt lgkmcnt(0)" ::: "memory");
; template <int MAP> __device__ __forceinline__ void transpose_matrix(const float* W, int K, int N, bf16* WT, LAS float* scr, int gw, int NGW, int lane) {
;     ...
;     for (int it = gw; it < nitems; it += NGW) {
;         const int kb = it / nblk, nb = it % nblk, n0 = nb * 32; int d = n0;
;         if (MAP == 1) d = n0 < 1024 ? n0 + 2048 : (n0 < 3072 ? n0 - 1024 : n0);
;         if (MAP == 2) d = 256 * (n0 >> 7) + (n0 & 127);
;         if (MAP == 3) d = 256 * (n0 >> 7) + 128 + (n0 & 127);
;         transpose_item(W, K, N, WT, d, scr, kb * 64, n0, lane);
	s_waitcnt vmcnt(0) lgkmcnt(0)
	ds_read2_b32 v[24:25], v22 offset1:8
	ds_read2_b32 v[28:29], v22 offset0:33 offset1:41
	ds_read2_b32 v[30:31], v22 offset0:66 offset1:74
	ds_read2_b32 v[32:33], v22 offset0:99 offset1:107
	ds_read2_b32 v[34:35], v22 offset0:132 offset1:140
	v_ashrrev_i32_e32 v11, 31, v10
	s_waitcnt lgkmcnt(4)
	v_bfe_u32 v5, v24, 16, 1
	v_add3_u32 v5, v24, v5, s72
	s_waitcnt lgkmcnt(3)
	v_bfe_u32 v9, v28, 16, 1
	v_lshrrev_b32_e32 v5, 16, v5
	v_add3_u32 v9, v28, v9, s72
	ds_read2_b32 v[36:37], v22 offset0:165 offset1:173
	v_lshl_add_u64 v[26:27], v[10:11], 1, v[6:7]
	v_and_or_b32 v10, v9, s73, v5
	s_waitcnt lgkmcnt(3)
	v_bfe_u32 v5, v30, 16, 1
	v_add3_u32 v5, v30, v5, s72
	s_waitcnt lgkmcnt(2)
	v_bfe_u32 v9, v32, 16, 1
	ds_read2_b32 v[38:39], v22 offset0:198 offset1:206
	v_lshrrev_b32_e32 v5, 16, v5
	v_add3_u32 v9, v32, v9, s72
	ds_read2_b32 v[40:41], v22 offset0:231 offset1:239
	v_and_or_b32 v11, v9, s73, v5
	s_waitcnt lgkmcnt(3)
	v_bfe_u32 v5, v34, 16, 1
	v_add3_u32 v5, v34, v5, s72
	s_waitcnt lgkmcnt(2)
	v_bfe_u32 v9, v36, 16, 1
	v_lshrrev_b32_e32 v5, 16, v5
	v_add3_u32 v9, v36, v9, s72
	v_and_or_b32 v12, v9, s73, v5
	s_waitcnt lgkmcnt(1)
	v_bfe_u32 v5, v38, 16, 1
	v_add3_u32 v5, v38, v5, s72
	s_waitcnt lgkmcnt(0)
	v_bfe_u32 v9, v40, 16, 1
	v_lshrrev_b32_e32 v5, 16, v5
	v_add3_u32 v9, v40, v9, s72
	v_or_b32_e32 v42, v8, v15
	v_and_or_b32 v13, v9, s73, v5
	v_ashrrev_i32_e32 v43, 31, v42
	v_bfe_u32 v5, v25, 16, 1
	v_lshlrev_b64 v[42:43], 12, v[42:43]
	v_add3_u32 v5, v25, v5, s72
	v_bfe_u32 v9, v29, 16, 1
	v_lshl_add_u64 v[42:43], v[26:27], 0, v[42:43]
	v_lshrrev_b32_e32 v5, 16, v5
	v_add3_u32 v9, v29, v9, s72
	global_store_dwordx4 v[42:43], v[10:13], off
	v_or_b32_e32 v24, v8, v16
	v_ashrrev_i32_e32 v25, 31, v24
	v_and_or_b32 v10, v9, s73, v5
	v_bfe_u32 v5, v31, 16, 1
	v_add3_u32 v5, v31, v5, s72
	v_bfe_u32 v9, v33, 16, 1
	v_lshrrev_b32_e32 v5, 16, v5
	v_add3_u32 v9, v33, v9, s72
	v_and_or_b32 v11, v9, s73, v5
	v_bfe_u32 v5, v35, 16, 1
	v_add3_u32 v5, v35, v5, s72
	v_bfe_u32 v9, v37, 16, 1
	v_lshrrev_b32_e32 v5, 16, v5
	v_add3_u32 v9, v37, v9, s72
	v_and_or_b32 v12, v9, s73, v5
	v_bfe_u32 v5, v39, 16, 1
	v_add3_u32 v5, v39, v5, s72
	v_bfe_u32 v9, v41, 16, 1
	v_lshrrev_b32_e32 v5, 16, v5
	v_add3_u32 v9, v41, v9, s72
	v_lshlrev_b64 v[24:25], 12, v[24:25]
	v_and_or_b32 v13, v9, s73, v5
	ds_read2_b32 v[28:29], v22 offset0:16 offset1:24
	v_lshl_add_u64 v[24:25], v[26:27], 0, v[24:25]
	global_store_dwordx4 v[24:25], v[10:13], off
	ds_read2_b32 v[24:25], v22 offset0:49 offset1:57
	ds_read2_b32 v[30:31], v22 offset0:82 offset1:90
	ds_read2_b32 v[32:33], v22 offset0:115 offset1:123
	s_waitcnt lgkmcnt(3)
	v_bfe_u32 v5, v28, 16, 1
	v_add3_u32 v5, v28, v5, s72
	s_waitcnt lgkmcnt(2)
	v_bfe_u32 v9, v24, 16, 1
	ds_read2_b32 v[34:35], v22 offset0:148 offset1:156
	v_lshrrev_b32_e32 v5, 16, v5
	v_add3_u32 v9, v24, v9, s72
	ds_read2_b32 v[36:37], v22 offset0:181 offset1:189
	v_and_or_b32 v10, v9, s73, v5
	s_waitcnt lgkmcnt(3)
	v_bfe_u32 v5, v30, 16, 1
	v_add3_u32 v5, v30, v5, s72
	s_waitcnt lgkmcnt(2)
	v_bfe_u32 v9, v32, 16, 1
	ds_read2_b32 v[38:39], v22 offset0:214 offset1:222
	v_lshrrev_b32_e32 v5, 16, v5
	v_add3_u32 v9, v32, v9, s72
	ds_read2_b32 v[40:41], v22 offset0:247 offset1:255
	v_and_or_b32 v11, v9, s73, v5
	s_waitcnt lgkmcnt(3)
	v_bfe_u32 v5, v34, 16, 1
	v_add3_u32 v5, v34, v5, s72
	s_waitcnt lgkmcnt(2)
	v_bfe_u32 v9, v36, 16, 1
	v_lshrrev_b32_e32 v5, 16, v5
	v_add3_u32 v9, v36, v9, s72
	v_and_or_b32 v12, v9, s73, v5
	s_waitcnt lgkmcnt(1)
	v_bfe_u32 v5, v38, 16, 1
	v_add3_u32 v5, v38, v5, s72
	s_waitcnt lgkmcnt(0)
	v_bfe_u32 v9, v40, 16, 1
	v_lshrrev_b32_e32 v5, 16, v5
	v_add3_u32 v9, v40, v9, s72
	v_or_b32_e32 v42, v8, v17
	v_and_or_b32 v13, v9, s73, v5
	v_ashrrev_i32_e32 v43, 31, v42
	v_bfe_u32 v5, v29, 16, 1
	v_lshlrev_b64 v[42:43], 12, v[42:43]
	v_add3_u32 v5, v29, v5, s72
	v_bfe_u32 v9, v25, 16, 1
	v_lshl_add_u64 v[42:43], v[26:27], 0, v[42:43]
	v_lshrrev_b32_e32 v5, 16, v5
	v_add3_u32 v9, v25, v9, s72
	global_store_dwordx4 v[42:43], v[10:13], off
	v_or_b32_e32 v8, v8, v18
	v_add_u32_e32 v23, s86, v23
	v_and_or_b32 v10, v9, s73, v5
	v_bfe_u32 v5, v31, 16, 1
	v_add3_u32 v5, v31, v5, s72
	v_bfe_u32 v9, v33, 16, 1
	v_lshrrev_b32_e32 v5, 16, v5
	v_add3_u32 v9, v33, v9, s72
	v_and_or_b32 v11, v9, s73, v5
	v_bfe_u32 v5, v35, 16, 1
	v_add3_u32 v5, v35, v5, s72
	v_bfe_u32 v9, v37, 16, 1
	v_lshrrev_b32_e32 v5, 16, v5
	v_add3_u32 v9, v37, v9, s72
	v_and_or_b32 v12, v9, s73, v5
	v_bfe_u32 v5, v39, 16, 1
	v_add3_u32 v5, v39, v5, s72
	v_bfe_u32 v9, v41, 16, 1
	v_lshrrev_b32_e32 v5, 16, v5
	v_add3_u32 v9, v41, v9, s72
	v_and_or_b32 v13, v9, s73, v5
	v_ashrrev_i32_e32 v9, 31, v8
	v_lshlrev_b64 v[8:9], 12, v[8:9]
	v_lshl_add_u64 v[8:9], v[26:27], 0, v[8:9]
	global_store_dwordx4 v[8:9], v[10:13], off
	s_waitcnt lgkmcnt(0)
	v_cmp_lt_i32_e32 vcc, s51, v23
	s_or_b64 s[4:5], vcc, s[4:5]
	s_andn2_b64 exec, exec, s[4:5]
	s_cbranch_execnz .LBB0_371

; __device__ __forceinline__ void transpose_item(const float* W, int K, int N, bf16* WT, int dst_row0, LAS float* scr, int k0, int n0, int lane) {
; #pragma unroll 8
;     for (int i = 0; i < 32; ++i) { const int kk = 2 * i + (lane >> 5); scr[kk * 33 + (lane & 31)] = W[(size_t)(k0 + kk) * N + n0 + (lane & 31)]; }
;     asm volatile("s_waitcnt vmcnt(0) lgkmcnt(0)" ::: "memory");
.LBB0_377:
	s_lshl_b32 s8, s3, 1
	s_lshl_b32 s7, s2, 1
	v_or_b32_e32 v11, s8, v0
	v_or_b32_e32 v9, s7, v1
	v_add_u32_e32 v26, v11, v10
	v_add_u32_e32 v24, v9, v5
	v_ashrrev_i32_e32 v27, 31, v26
	v_ashrrev_i32_e32 v25, 31, v24
	v_lshlrev_b64 v[26:27], 13, v[26:27]
	v_lshlrev_b64 v[24:25], 13, v[24:25]
	v_lshl_add_u64 v[26:27], v[12:13], 0, v[26:27]
	v_lshl_add_u64 v[24:25], v[12:13], 0, v[24:25]
	global_load_dword v100, v[26:27], off
	global_load_dword v101, v[24:25], off
	v_mad_u64_u32 v[120:121], s[10:11], v11, s55, v[4:5]
	v_mad_u64_u32 v[122:123], s[10:11], v9, s55, v[4:5]
	s_add_i32 s10, s8, 4
	s_add_i32 s9, s7, 4
	v_or_b32_e32 v11, s10, v0
	v_or_b32_e32 v9, s9, v1
	s_add_i32 s9, s7, 8
	s_add_i32 s3, s3, 16
	s_add_i32 s2, s2, 16
	s_add_i32 s6, s6, -16
	v_add_u32_e32 v26, v11, v10
	v_add_u32_e32 v24, v9, v5
	v_ashrrev_i32_e32 v27, 31, v26
	v_ashrrev_i32_e32 v25, 31, v24
	v_lshlrev_b64 v[26:27], 13, v[26:27]
	v_lshlrev_b64 v[24:25], 13, v[24:25]
	v_lshl_add_u64 v[26:27], v[12:13], 0, v[26:27]
	v_lshl_add_u64 v[24:25], v[12:13], 0, v[24:25]
	global_load_dword v102, v[26:27], off
	global_load_dword v103, v[24:25], off
	v_mad_u64_u32 v[124:125], s[10:11], v11, s55, v[4:5]
	v_mad_u64_u32 v[126:127], s[10:11], v9, s55, v[4:5]
	s_add_i32 s10, s8, 8
	s_nop 0
	v_or_b32_e32 v11, s10, v0
	v_or_b32_e32 v9, s9, v1
	s_add_i32 s9, s7, 12
	v_add_u32_e32 v26, v11, v10
	v_add_u32_e32 v24, v9, v5
	v_ashrrev_i32_e32 v27, 31, v26
	v_ashrrev_i32_e32 v25, 31, v24
	v_lshlrev_b64 v[26:27], 13, v[26:27]
	v_lshlrev_b64 v[24:25], 13, v[24:25]
	v_lshl_add_u64 v[26:27], v[12:13], 0, v[26:27]
	v_lshl_add_u64 v[24:25], v[12:13], 0, v[24:25]
	global_load_dword v104, v[26:27], off
	global_load_dword v105, v[24:25], off
	v_mad_u64_u32 v[128:129], s[10:11], v11, s55, v[4:5]
	v_mad_u64_u32 v[130:131], s[10:11], v9, s55, v[4:5]
	s_add_i32 s10, s8, 12
	s_nop 0
	v_or_b32_e32 v11, s10, v0
	v_or_b32_e32 v9, s9, v1
	s_add_i32 s9, s7, 16
	v_add_u32_e32 v26, v11, v10
	v_add_u32_e32 v24, v9, v5
	v_ashrrev_i32_e32 v27, 31, v26
	v_ashrrev_i32_e32 v25, 31, v24
	v_lshlrev_b64 v[26:27], 13, v[26:27]
	v_lshlrev_b64 v[24:25], 13, v[24:25]
	v_lshl_add_u64 v[26:27], v[12:13], 0, v[26:27]
	v_lshl_add_u64 v[24:25], v[12:13], 0, v[24:25]
	global_load_dword v106, v[26:27], off
	global_load_dword v107, v[24:25], off
	v_mad_u64_u32 v[132:133], s[10:11], v11, s55, v[4:5]
	v_mad_u64_u32 v[134:135], s[10:11], v9, s55, v[4:5]
	s_add_i32 s10, s8, 16
	s_nop 0
	v_or_b32_e32 v11, s10, v0
	v_or_b32_e32 v9, s9, v1
	s_add_i32 s9, s7, 20
	v_add_u32_e32 v26, v11, v10
	v_add_u32_e32 v24, v9, v5
	v_ashrrev_i32_e32 v27, 31, v26
	v_ashrrev_i32_e32 v25, 31, v24
	v_lshlrev_b64 v[26:27], 13, v[26:27]
	v_lshlrev_b64 v[24:25], 13, v[24:25]
	v_lshl_add_u64 v[26:27], v[12:13], 0, v[26:27]
	v_lshl_add_u64 v[24:25], v[12:13], 0, v[24:25]
	global_load_dword v108, v[26:27], off
	global_load_dword v109, v[24:25], off
	v_mad_u64_u32 v[136:137], s[10:11], v11, s55, v[4:5]
	v_mad_u64_u32 v[138:139], s[10:11], v9, s55, v[4:5]
	s_add_i32 s10, s8, 20
	s_nop 0
	v_or_b32_e32 v11, s10, v0
	v_or_b32_e32 v9, s9, v1
	s_add_i32 s9, s7, 24
	s_add_i32 s7, s7, 28
	v_add_u32_e32 v26, v11, v10
	v_add_u32_e32 v24, v9, v5
	v_ashrrev_i32_e32 v27, 31, v26
	v_ashrrev_i32_e32 v25, 31, v24
	v_lshlrev_b64 v[26:27], 13, v[26:27]
	v_lshlrev_b64 v[24:25], 13, v[24:25]
	v_lshl_add_u64 v[26:27], v[12:13], 0, v[26:27]
	v_lshl_add_u64 v[24:25], v[12:13], 0, v[24:25]
	global_load_dword v110, v[26:27], off
	global_load_dword v111, v[24:25], off
	v_mad_u64_u32 v[140:141], s[10:11], v11, s55, v[4:5]
	v_mad_u64_u32 v[142:143], s[10:11], v9, s55, v[4:5]
	s_add_i32 s10, s8, 24
	s_nop 0
	v_or_b32_e32 v11, s10, v0
	v_or_b32_e32 v9, s9, v1
	s_add_i32 s8, s8, 28
	s_cmp_lg_u32 s6, 0
	v_add_u32_e32 v26, v11, v10
	v_add_u32_e32 v24, v9, v5
	v_ashrrev_i32_e32 v27, 31, v26
	v_ashrrev_i32_e32 v25, 31, v24
	v_lshlrev_b64 v[26:27], 13, v[26:27]
	v_lshlrev_b64 v[24:25], 13, v[24:25]
	v_lshl_add_u64 v[26:27], v[12:13], 0, v[26:27]
	v_lshl_add_u64 v[24:25], v[12:13], 0, v[24:25]
	global_load_dword v112, v[26:27], off
	global_load_dword v113, v[24:25], off
	v_mad_u64_u32 v[144:145], s[10:11], v11, s55, v[4:5]
	v_mad_u64_u32 v[146:147], s[10:11], v9, s55, v[4:5]
	v_or_b32_e32 v11, s8, v0
	v_or_b32_e32 v9, s7, v1
	v_add_u32_e32 v26, v11, v10
	v_add_u32_e32 v24, v9, v5
	v_ashrrev_i32_e32 v27, 31, v26
	v_ashrrev_i32_e32 v25, 31, v24
	v_lshlrev_b64 v[26:27], 13, v[26:27]
	v_lshlrev_b64 v[24:25], 13, v[24:25]
	v_lshl_add_u64 v[26:27], v[12:13], 0, v[26:27]
	v_lshl_add_u64 v[24:25], v[12:13], 0, v[24:25]
	global_load_dword v114, v[26:27], off
	global_load_dword v115, v[24:25], off
	v_mad_u64_u32 v[148:149], s[8:9], v11, s55, v[4:5]
	v_mad_u64_u32 v[150:151], s[8:9], v9, s55, v[4:5]
	s_waitcnt vmcnt(0)
	ds_write_b32 v120, v100
	ds_write_b32 v122, v101
	ds_write_b32 v124, v102
	ds_write_b32 v126, v103
	ds_write_b32 v128, v104
	ds_write_b32 v130, v105
	ds_write_b32 v132, v106
	ds_write_b32 v134, v107
	ds_write_b32 v136, v108
	ds_write_b32 v138, v109
	ds_write_b32 v140, v110
	ds_write_b32 v142, v111
	ds_write_b32 v144, v112
	ds_write_b32 v146, v113
	ds_write_b32 v148, v114
	ds_write_b32 v150, v115
	s_cbranch_scc1 .LBB0_377
; #define LAS __attribute__((address_space(3)))
; __device__ __forceinline__ unsigned pk2(float lo, float hi) { return f2bf(lo) | (f2bf(hi) << 16); }
; __device__ __forceinline__ void transpose_item(const float* W, int K, int N, bf16* WT, int dst_row0, LAS float* scr, int k0, int n0, int lane) {
;     ...
;     const int c = lane & 7;
; #pragma unroll
;     for (int j = 0; j < 4; ++j) { const int n = (lane >> 3) + 8 * j; const LAS float* s = scr + (8 * c) * 33 + n;
;         u32x4 o; o.x = pk2(s[0 * 33], s[1 * 33]); o.y = pk2(s[2 * 33], s[3 * 33]); o.z = pk2(s[4 * 33], s[5 * 33]); o.w = pk2(s[6 * 33], s[7 * 33]);
;         *(u32x4*)(WT + (size_t)(dst_row0 + n) * K + k0 + 8 * c) = o; }
;     asm volatile("s_waitcnt lgkmcnt(0)" ::: "memory");
; template <int MAP> __device__ __forceinline__ void transpose_matrix(const float* W, int K, int N, bf16* WT, LAS float* scr, int gw, int NGW, int lane) {
;     ...
;     for (int it = gw; it < nitems; it += NGW) {
;         const int kb = it / nblk, nb = it % nblk, n0 = nb * 32; int d = n0;
;         if (MAP == 1) d = n0 < 1024 ? n0 + 2048 : (n0 < 3072 ? n0 - 1024 : n0);
;         if (MAP == 2) d = 256 * (n0 >> 7) + (n0 & 127);
;         if (MAP == 3) d = 256 * (n0 >> 7) + 128 + (n0 & 127);
;         transpose_item(W, K, N, WT, d, scr, kb * 64, n0, lane);
	s_waitcnt vmcnt(0) lgkmcnt(0)
	ds_read2_b32 v[24:25], v22 offset1:8
	ds_read2_b32 v[28:29], v22 offset0:33 offset1:41
	ds_read2_b32 v[30:31], v22 offset0:66 offset1:74
	ds_read2_b32 v[32:33], v22 offset0:99 offset1:107
	ds_read2_b32 v[34:35], v22 offset0:132 offset1:140
	v_ashrrev_i32_e32 v11, 31, v10
	s_waitcnt lgkmcnt(4)
	v_bfe_u32 v5, v24, 16, 1
	v_add3_u32 v5, v24, v5, s72
	s_waitcnt lgkmcnt(3)
	v_bfe_u32 v9, v28, 16, 1
	v_lshrrev_b32_e32 v5, 16, v5
	v_add3_u32 v9, v28, v9, s72
	ds_read2_b32 v[36:37], v22 offset0:165 offset1:173
	v_lshl_add_u64 v[26:27], v[10:11], 1, v[6:7]
	v_and_or_b32 v10, v9, s73, v5
	s_waitcnt lgkmcnt(3)
	v_bfe_u32 v5, v30, 16, 1
	v_add3_u32 v5, v30, v5, s72
	s_waitcnt lgkmcnt(2)
	v_bfe_u32 v9, v32, 16, 1
	ds_read2_b32 v[38:39], v22 offset0:198 offset1:206
	v_lshrrev_b32_e32 v5, 16, v5
	v_add3_u32 v9, v32, v9, s72
	ds_read2_b32 v[40:41], v22 offset0:231 offset1:239
	v_and_or_b32 v11, v9, s73, v5
	s_waitcnt lgkmcnt(3)
	v_bfe_u32 v5, v34, 16, 1
	v_add3_u32 v5, v34, v5, s72
	s_waitcnt lgkmcnt(2)
	v_bfe_u32 v9, v36, 16, 1
	v_lshrrev_b32_e32 v5, 16, v5
	v_add3_u32 v9, v36, v9, s72
	v_and_or_b32 v12, v9, s73, v5
	s_waitcnt lgkmcnt(1)
	v_bfe_u32 v5, v38, 16, 1
	v_add3_u32 v5, v38, v5, s72
	s_waitcnt lgkmcnt(0)
	v_bfe_u32 v9, v40, 16, 1
	v_lshrrev_b32_e32 v5, 16, v5
	v_add3_u32 v9, v40, v9, s72
	v_or_b32_e32 v42, v8, v15
	v_and_or_b32 v13, v9, s73, v5
	v_ashrrev_i32_e32 v43, 31, v42
	v_bfe_u32 v5, v25, 16, 1
	v_lshlrev_b64 v[42:43], 12, v[42:43]
	v_add3_u32 v5, v25, v5, s72
	v_bfe_u32 v9, v29, 16, 1
	v_lshl_add_u64 v[42:43], v[26:27], 0, v[42:43]
	v_lshrrev_b32_e32 v5, 16, v5
	v_add3_u32 v9, v29, v9, s72
	global_store_dwordx4 v[42:43], v[10:13], off
	v_or_b32_e32 v24, v8, v16
	v_ashrrev_i32_e32 v25, 31, v24
	v_and_or_b32 v10, v9, s73, v5
	v_bfe_u32 v5, v31, 16, 1
	v_add3_u32 v5, v31, v5, s72
	v_bfe_u32 v9, v33, 16, 1
	v_lshrrev_b32_e32 v5, 16, v5
	v_add3_u32 v9, v33, v9, s72
	v_and_or_b32 v11, v9, s73, v5
	v_bfe_u32 v5, v35, 16, 1
	v_add3_u32 v5, v35, v5, s72
	v_bfe_u32 v9, v37, 16, 1
	v_lshrrev_b32_e32 v5, 16, v5
	v_add3_u32 v9, v37, v9, s72
	v_and_or_b32 v12, v9, s73, v5
	v_bfe_u32 v5, v39, 16, 1
	v_add3_u32 v5, v39, v5, s72
	v_bfe_u32 v9, v41, 16, 1
	v_lshrrev_b32_e32 v5, 16, v5
	v_add3_u32 v9, v41, v9, s72
	v_lshlrev_b64 v[24:25], 12, v[24:25]
	v_and_or_b32 v13, v9, s73, v5
	ds_read2_b32 v[28:29], v22 offset0:16 offset1:24
	v_lshl_add_u64 v[24:25], v[26:27], 0, v[24:25]
	global_store_dwordx4 v[24:25], v[10:13], off
	ds_read2_b32 v[24:25], v22 offset0:49 offset1:57
	ds_read2_b32 v[30:31], v22 offset0:82 offset1:90
	ds_read2_b32 v[32:33], v22 offset0:115 offset1:123
	s_waitcnt lgkmcnt(3)
	v_bfe_u32 v5, v28, 16, 1
	v_add3_u32 v5, v28, v5, s72
	s_waitcnt lgkmcnt(2)
	v_bfe_u32 v9, v24, 16, 1
	ds_read2_b32 v[34:35], v22 offset0:148 offset1:156
	v_lshrrev_b32_e32 v5, 16, v5
	v_add3_u32 v9, v24, v9, s72
	ds_read2_b32 v[36:37], v22 offset0:181 offset1:189
	v_and_or_b32 v10, v9, s73, v5
	s_waitcnt lgkmcnt(3)
	v_bfe_u32 v5, v30, 16, 1
	v_add3_u32 v5, v30, v5, s72
	s_waitcnt lgkmcnt(2)
	v_bfe_u32 v9, v32, 16, 1
	ds_read2_b32 v[38:39], v22 offset0:214 offset1:222
	v_lshrrev_b32_e32 v5, 16, v5
	v_add3_u32 v9, v32, v9, s72
	ds_read2_b32 v[40:41], v22 offset0:247 offset1:255
	v_and_or_b32 v11, v9, s73, v5
	s_waitcnt lgkmcnt(3)
	v_bfe_u32 v5, v34, 16, 1
	v_add3_u32 v5, v34, v5, s72
	s_waitcnt lgkmcnt(2)
	v_bfe_u32 v9, v36, 16, 1
	v_lshrrev_b32_e32 v5, 16, v5
	v_add3_u32 v9, v36, v9, s72
	v_and_or_b32 v12, v9, s73, v5
	s_waitcnt lgkmcnt(1)
	v_bfe_u32 v5, v38, 16, 1
	v_add3_u32 v5, v38, v5, s72
	s_waitcnt lgkmcnt(0)
	v_bfe_u32 v9, v40, 16, 1
	v_lshrrev_b32_e32 v5, 16, v5
	v_add3_u32 v9, v40, v9, s72
	v_or_b32_e32 v42, v8, v17
	v_and_or_b32 v13, v9, s73, v5
	v_ashrrev_i32_e32 v43, 31, v42
	v_bfe_u32 v5, v29, 16, 1
	v_lshlrev_b64 v[42:43], 12, v[42:43]
	v_add3_u32 v5, v29, v5, s72
	v_bfe_u32 v9, v25, 16, 1
	v_lshl_add_u64 v[42:43], v[26:27], 0, v[42:43]
	v_lshrrev_b32_e32 v5, 16, v5
	v_add3_u32 v9, v25, v9, s72
	global_store_dwordx4 v[42:43], v[10:13], off
	v_or_b32_e32 v8, v8, v18
	v_add_u32_e32 v23, s86, v23
	v_and_or_b32 v10, v9, s73, v5
	v_bfe_u32 v5, v31, 16, 1
	v_add3_u32 v5, v31, v5, s72
	v_bfe_u32 v9, v33, 16, 1
	v_lshrrev_b32_e32 v5, 16, v5
	v_add3_u32 v9, v33, v9, s72
	v_and_or_b32 v11, v9, s73, v5
	v_bfe_u32 v5, v35, 16, 1
	v_add3_u32 v5, v35, v5, s72
	v_bfe_u32 v9, v37, 16, 1
	v_lshrrev_b32_e32 v5, 16, v5
	v_add3_u32 v9, v37, v9, s72
	v_and_or_b32 v12, v9, s73, v5
	v_bfe_u32 v5, v39, 16, 1
	v_add3_u32 v5, v39, v5, s72
	v_bfe_u32 v9, v41, 16, 1
	v_lshrrev_b32_e32 v5, 16, v5
	v_add3_u32 v9, v41, v9, s72
	v_and_or_b32 v13, v9, s73, v5
	v_ashrrev_i32_e32 v9, 31, v8
	v_lshlrev_b64 v[8:9], 12, v[8:9]
	v_lshl_add_u64 v[8:9], v[26:27], 0, v[8:9]
	global_store_dwordx4 v[8:9], v[10:13], off
	s_waitcnt lgkmcnt(0)
	v_cmp_lt_i32_e32 vcc, s82, v23
	s_or_b64 s[4:5], vcc, s[4:5]
	s_andn2_b64 exec, exec, s[4:5]
	s_cbranch_execnz .LBB0_376

; __device__ __forceinline__ void transpose_item(const float* W, int K, int N, bf16* WT, int dst_row0, LAS float* scr, int k0, int n0, int lane) {
; #pragma unroll 8
;     for (int i = 0; i < 32; ++i) { const int kk = 2 * i + (lane >> 5); scr[kk * 33 + (lane & 31)] = W[(size_t)(k0 + kk) * N + n0 + (lane & 31)]; }
;     asm volatile("s_waitcnt vmcnt(0) lgkmcnt(0)" ::: "memory");
.LBB0_382:
	s_lshl_b32 s10, s1, 1
	s_lshl_b32 s3, s0, 1
	v_or_b32_e32 v28, s10, v0
	v_or_b32_e32 v11, s3, v1
	v_add_u32_e32 v24, v28, v8
	v_add_u32_e32 v26, v11, v5
	v_mad_i64_i32 v[24:25], s[12:13], v24, s56, v[12:13]
	v_mad_i64_i32 v[26:27], s[12:13], v26, s56, v[12:13]
	global_load_dword v100, v[24:25], off
	global_load_dword v101, v[26:27], off
	v_mad_u64_u32 v[120:121], s[12:13], v28, s55, v[4:5]
	v_mad_u64_u32 v[122:123], s[12:13], v11, s55, v[4:5]
	s_add_i32 s12, s10, 4
	s_add_i32 s11, s3, 4
	v_or_b32_e32 v28, s12, v0
	v_or_b32_e32 v11, s11, v1
	s_add_i32 s11, s3, 8
	s_add_i32 s1, s1, 16
	s_add_i32 s0, s0, 16
	s_add_i32 s2, s2, -16
	v_add_u32_e32 v24, v28, v8
	v_add_u32_e32 v26, v11, v5
	v_mad_i64_i32 v[24:25], s[12:13], v24, s56, v[12:13]
	v_mad_i64_i32 v[26:27], s[12:13], v26, s56, v[12:13]
	global_load_dword v102, v[24:25], off
	global_load_dword v103, v[26:27], off
	v_mad_u64_u32 v[124:125], s[12:13], v28, s55, v[4:5]
	v_mad_u64_u32 v[126:127], s[12:13], v11, s55, v[4:5]
	s_add_i32 s12, s10, 8
	s_nop 0
	v_or_b32_e32 v28, s12, v0
	v_or_b32_e32 v11, s11, v1
	s_add_i32 s11, s3, 12
	v_add_u32_e32 v24, v28, v8
	v_add_u32_e32 v26, v11, v5
	v_mad_i64_i32 v[24:25], s[12:13], v24, s56, v[12:13]
	v_mad_i64_i32 v[26:27], s[12:13], v26, s56, v[12:13]
	global_load_dword v104, v[24:25], off
	global_load_dword v105, v[26:27], off
	v_mad_u64_u32 v[128:129], s[12:13], v28, s55, v[4:5]
	v_mad_u64_u32 v[130:131], s[12:13], v11, s55, v[4:5]
	s_add_i32 s12, s10, 12
	s_nop 0
	v_or_b32_e32 v28, s12, v0
	v_or_b32_e32 v11, s11, v1
	s_add_i32 s11, s3, 16
	v_add_u32_e32 v24, v28, v8
	v_add_u32_e32 v26, v11, v5
	v_mad_i64_i32 v[24:25], s[12:13], v24, s56, v[12:13]
	v_mad_i64_i32 v[26:27], s[12:13], v26, s56, v[12:13]
	global_load_dword v106, v[24:25], off
	global_load_dword v107, v[26:27], off
	v_mad_u64_u32 v[132:133], s[12:13], v28, s55, v[4:5]
	v_mad_u64_u32 v[134:135], s[12:13], v11, s55, v[4:5]
	s_add_i32 s12, s10, 16
	s_nop 0
	v_or_b32_e32 v28, s12, v0
	v_or_b32_e32 v11, s11, v1
	s_add_i32 s11, s3, 20
	v_add_u32_e32 v24, v28, v8
	v_add_u32_e32 v26, v11, v5
	v_mad_i64_i32 v[24:25], s[12:13], v24, s56, v[12:13]
	v_mad_i64_i32 v[26:27], s[12:13], v26, s56, v[12:13]
	global_load_dword v108, v[24:25], off
	global_load_dword v109, v[26:27], off
	v_mad_u64_u32 v[136:137], s[12:13], v28, s55, v[4:5]
	v_mad_u64_u32 v[138:139], s[12:13], v11, s55, v[4:5]
	s_add_i32 s12, s10, 20
	s_nop 0
	v_or_b32_e32 v28, s12, v0
	v_or_b32_e32 v11, s11, v1
	s_add_i32 s11, s3, 24
	s_add_i32 s3, s3, 28
	v_add_u32_e32 v24, v28, v8
	v_add_u32_e32 v26, v11, v5
	v_mad_i64_i32 v[24:25], s[12:13], v24, s56, v[12:13]
	v_mad_i64_i32 v[26:27], s[12:13], v26, s56, v[12:13]
	global_load_dword v110, v[24:25], off
	global_load_dword v111, v[26:27], off
	v_mad_u64_u32 v[140:141], s[12:13], v28, s55, v[4:5]
	v_mad_u64_u32 v[142:143], s[12:13], v11, s55, v[4:5]
	s_add_i32 s12, s10, 24
	s_nop 0
	v_or_b32_e32 v28, s12, v0
	v_or_b32_e32 v11, s11, v1
	s_add_i32 s10, s10, 28
	s_cmp_lg_u32 s2, 0
	v_add_u32_e32 v24, v28, v8
	v_add_u32_e32 v26, v11, v5
	v_mad_i64_i32 v[24:25], s[12:13], v24, s56, v[12:13]
	v_mad_i64_i32 v[26:27], s[12:13], v26, s56, v[12:13]
	global_load_dword v112, v[24:25], off
	global_load_dword v113, v[26:27], off
	v_mad_u64_u32 v[144:145], s[12:13], v28, s55, v[4:5]
	v_or_b32_e32 v28, s10, v0
	v_mad_u64_u32 v[146:147], s[12:13], v11, s55, v[4:5]
	v_or_b32_e32 v11, s3, v1
	v_add_u32_e32 v24, v28, v8
	v_add_u32_e32 v26, v11, v5
	v_mad_i64_i32 v[24:25], s[10:11], v24, s56, v[12:13]
	v_mad_i64_i32 v[26:27], s[10:11], v26, s56, v[12:13]
	global_load_dword v114, v[24:25], off
	global_load_dword v115, v[26:27], off
	v_mad_u64_u32 v[148:149], s[10:11], v28, s55, v[4:5]
	v_mad_u64_u32 v[150:151], s[10:11], v11, s55, v[4:5]
	s_waitcnt vmcnt(0)
	ds_write_b32 v120, v100
	ds_write_b32 v122, v101
	ds_write_b32 v124, v102
	ds_write_b32 v126, v103
	ds_write_b32 v128, v104
	ds_write_b32 v130, v105
	ds_write_b32 v132, v106
	ds_write_b32 v134, v107
	ds_write_b32 v136, v108
	ds_write_b32 v138, v109
	ds_write_b32 v140, v110
	ds_write_b32 v142, v111
	ds_write_b32 v144, v112
	ds_write_b32 v146, v113
	ds_write_b32 v148, v114
	ds_write_b32 v150, v115
	s_cbranch_scc1 .LBB0_382
; #define LAS __attribute__((address_space(3)))
; __device__ __forceinline__ unsigned pk2(float lo, float hi) { return f2bf(lo) | (f2bf(hi) << 16); }
; __device__ __forceinline__ void transpose_item(const float* W, int K, int N, bf16* WT, int dst_row0, LAS float* scr, int k0, int n0, int lane) {
;     ...
;     const int c = lane & 7;
; #pragma unroll
;     for (int j = 0; j < 4; ++j) { const int n = (lane >> 3) + 8 * j; const LAS float* s = scr + (8 * c) * 33 + n;
;         u32x4 o; o.x = pk2(s[0 * 33], s[1 * 33]); o.y = pk2(s[2 * 33], s[3 * 33]); o.z = pk2(s[4 * 33], s[5 * 33]); o.w = pk2(s[6 * 33], s[7 * 33]);
;         *(u32x4*)(WT + (size_t)(dst_row0 + n) * K + k0 + 8 * c) = o; }
;     asm volatile("s_waitcnt lgkmcnt(0)" ::: "memory");
; template <int MAP> __device__ __forceinline__ void transpose_matrix(const float* W, int K, int N, bf16* WT, LAS float* scr, int gw, int NGW, int lane) {
;     ...
;         if (MAP == 1) d = n0 < 1024 ? n0 + 2048 : (n0 < 3072 ? n0 - 1024 : n0);
;         if (MAP == 2) d = 256 * (n0 >> 7) + (n0 & 127);
;         if (MAP == 3) d = 256 * (n0 >> 7) + 128 + (n0 & 127);
;         transpose_item(W, K, N, WT, d, scr, kb * 64, n0, lane);
	s_waitcnt vmcnt(0) lgkmcnt(0)
	ds_read2_b32 v[12:13], v22 offset1:8
	ds_read2_b32 v[26:27], v22 offset0:33 offset1:41
	v_lshlrev_b32_e32 v5, 6, v9
	v_and_b32_e32 v9, 0x60, v10
	s_movk_i32 s0, 0xff00
	ds_read2_b32 v[28:29], v22 offset0:66 offset1:74
	v_and_or_b32 v5, v5, s0, v9
	v_ashrrev_i32_e32 v9, 31, v8
	ds_read2_b32 v[30:31], v22 offset0:99 offset1:107
	v_lshl_add_u64 v[24:25], v[8:9], 1, v[6:7]
	s_waitcnt lgkmcnt(3)
	v_bfe_u32 v8, v12, 16, 1
	v_add3_u32 v8, v12, v8, s72
	s_waitcnt lgkmcnt(2)
	v_bfe_u32 v9, v26, 16, 1
	ds_read2_b32 v[32:33], v22 offset0:132 offset1:140
	v_lshrrev_b32_e32 v8, 16, v8
	v_add3_u32 v9, v26, v9, s72
	ds_read2_b32 v[34:35], v22 offset0:165 offset1:173
	v_and_or_b32 v8, v9, s73, v8
	s_waitcnt lgkmcnt(3)
	v_bfe_u32 v9, v28, 16, 1
	v_add3_u32 v9, v28, v9, s72
	s_waitcnt lgkmcnt(2)
	v_bfe_u32 v10, v30, 16, 1
	ds_read2_b32 v[36:37], v22 offset0:198 offset1:206
	v_lshrrev_b32_e32 v9, 16, v9
	v_add3_u32 v10, v30, v10, s72
	ds_read2_b32 v[38:39], v22 offset0:231 offset1:239
	v_and_or_b32 v9, v10, s73, v9
	s_waitcnt lgkmcnt(3)
	v_bfe_u32 v10, v32, 16, 1
	v_add3_u32 v10, v32, v10, s72
	s_waitcnt lgkmcnt(2)
	v_bfe_u32 v11, v34, 16, 1
	v_lshrrev_b32_e32 v10, 16, v10
	v_add3_u32 v11, v34, v11, s72
	v_and_or_b32 v10, v11, s73, v10
	s_waitcnt lgkmcnt(1)
	v_bfe_u32 v11, v36, 16, 1
	v_or_b32_e32 v40, v5, v15
	v_add3_u32 v11, v36, v11, s72
	s_waitcnt lgkmcnt(0)
	v_bfe_u32 v12, v38, 16, 1
	v_ashrrev_i32_e32 v41, 31, v40
	v_lshrrev_b32_e32 v11, 16, v11
	v_add3_u32 v12, v38, v12, s72
	v_lshlrev_b64 v[40:41], 12, v[40:41]
	v_and_or_b32 v11, v12, s73, v11
	v_lshl_add_u64 v[40:41], v[24:25], 0, v[40:41]
	global_store_dwordx4 v[40:41], v[8:11], off
	v_bfe_u32 v12, v39, 16, 1
	v_add3_u32 v12, v39, v12, s72
	v_bfe_u32 v8, v13, 16, 1
	v_add3_u32 v8, v13, v8, s72
	v_bfe_u32 v9, v27, 16, 1
	v_lshrrev_b32_e32 v8, 16, v8
	v_add3_u32 v9, v27, v9, s72
	v_and_or_b32 v8, v9, s73, v8
	v_bfe_u32 v9, v29, 16, 1
	v_add3_u32 v9, v29, v9, s72
	v_bfe_u32 v10, v31, 16, 1
	v_lshrrev_b32_e32 v9, 16, v9
	v_add3_u32 v10, v31, v10, s72
	v_and_or_b32 v9, v10, s73, v9
	v_bfe_u32 v10, v33, 16, 1
	v_add3_u32 v10, v33, v10, s72
	v_bfe_u32 v11, v35, 16, 1
	v_lshrrev_b32_e32 v10, 16, v10
	v_add3_u32 v11, v35, v11, s72
	v_and_or_b32 v10, v11, s73, v10
	v_bfe_u32 v11, v37, 16, 1
	v_add3_u32 v11, v37, v11, s72
	v_lshrrev_b32_e32 v11, 16, v11
	v_and_or_b32 v11, v12, s73, v11
	v_or_b32_e32 v12, v5, v16
	v_ashrrev_i32_e32 v13, 31, v12
	v_lshlrev_b64 v[12:13], 12, v[12:13]
	ds_read2_b32 v[26:27], v22 offset0:16 offset1:24
	v_lshl_add_u64 v[12:13], v[24:25], 0, v[12:13]
	global_store_dwordx4 v[12:13], v[8:11], off
	ds_read2_b32 v[12:13], v22 offset0:49 offset1:57
	ds_read2_b32 v[28:29], v22 offset0:82 offset1:90
	ds_read2_b32 v[30:31], v22 offset0:115 offset1:123
	s_waitcnt lgkmcnt(3)
	v_bfe_u32 v8, v26, 16, 1
	v_add3_u32 v8, v26, v8, s72
	s_waitcnt lgkmcnt(2)
	v_bfe_u32 v9, v12, 16, 1
	ds_read2_b32 v[32:33], v22 offset0:148 offset1:156
	v_lshrrev_b32_e32 v8, 16, v8
	v_add3_u32 v9, v12, v9, s72
	ds_read2_b32 v[34:35], v22 offset0:181 offset1:189
	v_and_or_b32 v8, v9, s73, v8
	s_waitcnt lgkmcnt(3)
	v_bfe_u32 v9, v28, 16, 1
	v_add3_u32 v9, v28, v9, s72
	s_waitcnt lgkmcnt(2)
	v_bfe_u32 v10, v30, 16, 1
	ds_read2_b32 v[36:37], v22 offset0:214 offset1:222
	v_lshrrev_b32_e32 v9, 16, v9
	v_add3_u32 v10, v30, v10, s72
	ds_read2_b32 v[38:39], v22 offset0:247 offset1:255
	v_and_or_b32 v9, v10, s73, v9
	s_waitcnt lgkmcnt(3)
	v_bfe_u32 v10, v32, 16, 1
	v_add3_u32 v10, v32, v10, s72
	s_waitcnt lgkmcnt(2)
	v_bfe_u32 v11, v34, 16, 1
	v_lshrrev_b32_e32 v10, 16, v10
	v_add3_u32 v11, v34, v11, s72
	v_and_or_b32 v10, v11, s73, v10
	s_waitcnt lgkmcnt(1)
	v_bfe_u32 v11, v36, 16, 1
	v_or_b32_e32 v40, v5, v17
	v_add3_u32 v11, v36, v11, s72
	s_waitcnt lgkmcnt(0)
	v_bfe_u32 v12, v38, 16, 1
	v_ashrrev_i32_e32 v41, 31, v40
	v_lshrrev_b32_e32 v11, 16, v11
	v_add3_u32 v12, v38, v12, s72
	v_lshlrev_b64 v[40:41], 12, v[40:41]
	v_and_or_b32 v11, v12, s73, v11
	v_lshl_add_u64 v[40:41], v[24:25], 0, v[40:41]
	global_store_dwordx4 v[40:41], v[8:11], off
	v_bfe_u32 v12, v39, 16, 1
	v_add3_u32 v12, v39, v12, s72
	v_bfe_u32 v8, v27, 16, 1
	v_add3_u32 v8, v27, v8, s72
	v_bfe_u32 v9, v13, 16, 1
	v_lshrrev_b32_e32 v8, 16, v8
	v_add3_u32 v9, v13, v9, s72
	v_and_or_b32 v8, v9, s73, v8
	v_bfe_u32 v9, v29, 16, 1
	v_add3_u32 v9, v29, v9, s72
	v_bfe_u32 v10, v31, 16, 1
	v_lshrrev_b32_e32 v9, 16, v9
	v_add3_u32 v10, v31, v10, s72
	v_and_or_b32 v9, v10, s73, v9
	v_bfe_u32 v10, v33, 16, 1
	v_add3_u32 v10, v33, v10, s72
	v_bfe_u32 v11, v35, 16, 1
	v_lshrrev_b32_e32 v10, 16, v10
	v_add3_u32 v11, v35, v11, s72
	v_and_or_b32 v10, v11, s73, v10
	v_bfe_u32 v11, v37, 16, 1
	v_add3_u32 v11, v37, v11, s72
	v_lshrrev_b32_e32 v11, 16, v11
	v_and_or_b32 v11, v12, s73, v11
	v_or_b32_e32 v12, v5, v18
	v_ashrrev_i32_e32 v13, 31, v12
	v_lshlrev_b64 v[12:13], 12, v[12:13]
	v_lshl_add_u64 v[12:13], v[24:25], 0, v[12:13]
	global_store_dwordx4 v[12:13], v[8:11], off
	v_add_u32_e32 v23, s86, v23
	s_movk_i32 s0, 0x15ff
	s_waitcnt lgkmcnt(0)
	v_cmp_lt_i32_e64 s[0:1], s0, v23
	s_or_b64 s[8:9], s[0:1], s[8:9]
	s_andn2_b64 exec, exec, s[8:9]
	s_cbranch_execnz .LBB0_381

; __device__ __forceinline__ void transpose_item(const float* W, int K, int N, bf16* WT, int dst_row0, LAS float* scr, int k0, int n0, int lane) {
; #pragma unroll 8
;     for (int i = 0; i < 32; ++i) { const int kk = 2 * i + (lane >> 5); scr[kk * 33 + (lane & 31)] = W[(size_t)(k0 + kk) * N + n0 + (lane & 31)]; }
;     asm volatile("s_waitcnt vmcnt(0) lgkmcnt(0)" ::: "memory");
.LBB0_387:
	s_lshl_b32 s8, s1, 1
	s_lshl_b32 s3, s0, 1
	v_or_b32_e32 v28, s8, v0
	v_or_b32_e32 v11, s3, v1
	v_add_u32_e32 v24, v28, v8
	v_add_u32_e32 v26, v11, v5
	v_mad_i64_i32 v[24:25], s[10:11], v24, s56, v[12:13]
	v_mad_i64_i32 v[26:27], s[10:11], v26, s56, v[12:13]
	global_load_dword v100, v[24:25], off
	global_load_dword v101, v[26:27], off
	v_mad_u64_u32 v[120:121], s[10:11], v28, s55, v[4:5]
	v_mad_u64_u32 v[122:123], s[10:11], v11, s55, v[4:5]
	s_add_i32 s10, s8, 4
	s_add_i32 s9, s3, 4
	v_or_b32_e32 v28, s10, v0
	v_or_b32_e32 v11, s9, v1
	s_add_i32 s9, s3, 8
	s_add_i32 s1, s1, 16
	s_add_i32 s0, s0, 16
	s_add_i32 s2, s2, -16
	v_add_u32_e32 v24, v28, v8
	v_add_u32_e32 v26, v11, v5
	v_mad_i64_i32 v[24:25], s[10:11], v24, s56, v[12:13]
	v_mad_i64_i32 v[26:27], s[10:11], v26, s56, v[12:13]
	global_load_dword v102, v[24:25], off
	global_load_dword v103, v[26:27], off
	v_mad_u64_u32 v[124:125], s[10:11], v28, s55, v[4:5]
	v_mad_u64_u32 v[126:127], s[10:11], v11, s55, v[4:5]
	s_add_i32 s10, s8, 8
	s_nop 0
	v_or_b32_e32 v28, s10, v0
	v_or_b32_e32 v11, s9, v1
	s_add_i32 s9, s3, 12
	v_add_u32_e32 v24, v28, v8
	v_add_u32_e32 v26, v11, v5
	v_mad_i64_i32 v[24:25], s[10:11], v24, s56, v[12:13]
	v_mad_i64_i32 v[26:27], s[10:11], v26, s56, v[12:13]
	global_load_dword v104, v[24:25], off
	global_load_dword v105, v[26:27], off
	v_mad_u64_u32 v[128:129], s[10:11], v28, s55, v[4:5]
	v_mad_u64_u32 v[130:131], s[10:11], v11, s55, v[4:5]
	s_add_i32 s10, s8, 12
	s_nop 0
	v_or_b32_e32 v28, s10, v0
	v_or_b32_e32 v11, s9, v1
	s_add_i32 s9, s3, 16
	v_add_u32_e32 v24, v28, v8
	v_add_u32_e32 v26, v11, v5
	v_mad_i64_i32 v[24:25], s[10:11], v24, s56, v[12:13]
	v_mad_i64_i32 v[26:27], s[10:11], v26, s56, v[12:13]
	global_load_dword v106, v[24:25], off
	global_load_dword v107, v[26:27], off
	v_mad_u64_u32 v[132:133], s[10:11], v28, s55, v[4:5]
	v_mad_u64_u32 v[134:135], s[10:11], v11, s55, v[4:5]
	s_add_i32 s10, s8, 16
	s_nop 0
	v_or_b32_e32 v28, s10, v0
	v_or_b32_e32 v11, s9, v1
	s_add_i32 s9, s3, 20
	v_add_u32_e32 v24, v28, v8
	v_add_u32_e32 v26, v11, v5
	v_mad_i64_i32 v[24:25], s[10:11], v24, s56, v[12:13]
	v_mad_i64_i32 v[26:27], s[10:11], v26, s56, v[12:13]
	global_load_dword v108, v[24:25], off
	global_load_dword v109, v[26:27], off
	v_mad_u64_u32 v[136:137], s[10:11], v28, s55, v[4:5]
	v_mad_u64_u32 v[138:139], s[10:11], v11, s55, v[4:5]
	s_add_i32 s10, s8, 20
	s_nop 0
	v_or_b32_e32 v28, s10, v0
	v_or_b32_e32 v11, s9, v1
	s_add_i32 s9, s3, 24
	s_add_i32 s3, s3, 28
	v_add_u32_e32 v24, v28, v8
	v_add_u32_e32 v26, v11, v5
	v_mad_i64_i32 v[24:25], s[10:11], v24, s56, v[12:13]
	v_mad_i64_i32 v[26:27], s[10:11], v26, s56, v[12:13]
	global_load_dword v110, v[24:25], off
	global_load_dword v111, v[26:27], off
	v_mad_u64_u32 v[140:141], s[10:11], v28, s55, v[4:5]
	v_mad_u64_u32 v[142:143], s[10:11], v11, s55, v[4:5]
	s_add_i32 s10, s8, 24
	s_nop 0
	v_or_b32_e32 v28, s10, v0
	v_or_b32_e32 v11, s9, v1
	s_add_i32 s8, s8, 28
	s_cmp_lg_u32 s2, 0
	v_add_u32_e32 v24, v28, v8
	v_add_u32_e32 v26, v11, v5
	v_mad_i64_i32 v[24:25], s[10:11], v24, s56, v[12:13]
	v_mad_i64_i32 v[26:27], s[10:11], v26, s56, v[12:13]
	global_load_dword v112, v[24:25], off
	global_load_dword v113, v[26:27], off
	v_mad_u64_u32 v[144:145], s[10:11], v28, s55, v[4:5]
	v_or_b32_e32 v28, s8, v0
	v_mad_u64_u32 v[146:147], s[10:11], v11, s55, v[4:5]
	v_or_b32_e32 v11, s3, v1
	v_add_u32_e32 v24, v28, v8
	v_add_u32_e32 v26, v11, v5
	v_mad_i64_i32 v[24:25], s[8:9], v24, s56, v[12:13]
	v_mad_i64_i32 v[26:27], s[8:9], v26, s56, v[12:13]
	global_load_dword v114, v[24:25], off
	global_load_dword v115, v[26:27], off
	v_mad_u64_u32 v[148:149], s[8:9], v28, s55, v[4:5]
	v_mad_u64_u32 v[150:151], s[8:9], v11, s55, v[4:5]
	s_waitcnt vmcnt(0)
	ds_write_b32 v120, v100
	ds_write_b32 v122, v101
	ds_write_b32 v124, v102
	ds_write_b32 v126, v103
	ds_write_b32 v128, v104
	ds_write_b32 v130, v105
	ds_write_b32 v132, v106
	ds_write_b32 v134, v107
	ds_write_b32 v136, v108
	ds_write_b32 v138, v109
	ds_write_b32 v140, v110
	ds_write_b32 v142, v111
	ds_write_b32 v144, v112
	ds_write_b32 v146, v113
	ds_write_b32 v148, v114
	ds_write_b32 v150, v115
	s_cbranch_scc1 .LBB0_387
; #define LAS __attribute__((address_space(3)))
; __device__ __forceinline__ unsigned pk2(float lo, float hi) { return f2bf(lo) | (f2bf(hi) << 16); }
; __device__ __forceinline__ void transpose_item(const float* W, int K, int N, bf16* WT, int dst_row0, LAS float* scr, int k0, int n0, int lane) {
;     ...
;     const int c = lane & 7;
; #pragma unroll
;     for (int j = 0; j < 4; ++j) { const int n = (lane >> 3) + 8 * j; const LAS float* s = scr + (8 * c) * 33 + n;
;         u32x4 o; o.x = pk2(s[0 * 33], s[1 * 33]); o.y = pk2(s[2 * 33], s[3 * 33]); o.z = pk2(s[4 * 33], s[5 * 33]); o.w = pk2(s[6 * 33], s[7 * 33]);
;         *(u32x4*)(WT + (size_t)(dst_row0 + n) * K + k0 + 8 * c) = o; }
;     asm volatile("s_waitcnt lgkmcnt(0)" ::: "memory");
; template <int MAP> __device__ __forceinline__ void transpose_matrix(const float* W, int K, int N, bf16* WT, LAS float* scr, int gw, int NGW, int lane) {
;     ...
;         if (MAP == 1) d = n0 < 1024 ? n0 + 2048 : (n0 < 3072 ? n0 - 1024 : n0);
;         if (MAP == 2) d = 256 * (n0 >> 7) + (n0 & 127);
;         if (MAP == 3) d = 256 * (n0 >> 7) + 128 + (n0 & 127);
;         transpose_item(W, K, N, WT, d, scr, kb * 64, n0, lane);
	s_waitcnt vmcnt(0) lgkmcnt(0)
	ds_read2_b32 v[12:13], v22 offset1:8
	ds_read2_b32 v[26:27], v22 offset0:33 offset1:41
	v_lshlrev_b32_e32 v5, 6, v9
	v_and_b32_e32 v5, 0xffffff00, v5
	v_and_b32_e32 v9, 0x60, v10
	s_movk_i32 s0, 0x80
	ds_read2_b32 v[28:29], v22 offset0:66 offset1:74
	v_or3_b32 v5, v9, v5, s0
	v_ashrrev_i32_e32 v9, 31, v8
	ds_read2_b32 v[30:31], v22 offset0:99 offset1:107
	v_lshl_add_u64 v[24:25], v[8:9], 1, v[6:7]
	s_waitcnt lgkmcnt(3)
	v_bfe_u32 v8, v12, 16, 1
	v_add3_u32 v8, v12, v8, s72
	s_waitcnt lgkmcnt(2)
	v_bfe_u32 v9, v26, 16, 1
	ds_read2_b32 v[32:33], v22 offset0:132 offset1:140
	v_lshrrev_b32_e32 v8, 16, v8
	v_add3_u32 v9, v26, v9, s72
	ds_read2_b32 v[34:35], v22 offset0:165 offset1:173
	v_and_or_b32 v8, v9, s73, v8
	s_waitcnt lgkmcnt(3)
	v_bfe_u32 v9, v28, 16, 1
	v_add3_u32 v9, v28, v9, s72
	s_waitcnt lgkmcnt(2)
	v_bfe_u32 v10, v30, 16, 1
	ds_read2_b32 v[36:37], v22 offset0:198 offset1:206
	v_lshrrev_b32_e32 v9, 16, v9
	v_add3_u32 v10, v30, v10, s72
	ds_read2_b32 v[38:39], v22 offset0:231 offset1:239
	v_and_or_b32 v9, v10, s73, v9
	s_waitcnt lgkmcnt(3)
	v_bfe_u32 v10, v32, 16, 1
	v_add3_u32 v10, v32, v10, s72
	s_waitcnt lgkmcnt(2)
	v_bfe_u32 v11, v34, 16, 1
	v_lshrrev_b32_e32 v10, 16, v10
	v_add3_u32 v11, v34, v11, s72
	v_and_or_b32 v10, v11, s73, v10
	s_waitcnt lgkmcnt(1)
	v_bfe_u32 v11, v36, 16, 1
	v_or_b32_e32 v40, v5, v15
	v_add3_u32 v11, v36, v11, s72
	s_waitcnt lgkmcnt(0)
	v_bfe_u32 v12, v38, 16, 1
	v_ashrrev_i32_e32 v41, 31, v40
	v_lshrrev_b32_e32 v11, 16, v11
	v_add3_u32 v12, v38, v12, s72
	v_lshlrev_b64 v[40:41], 12, v[40:41]
	v_and_or_b32 v11, v12, s73, v11
	v_lshl_add_u64 v[40:41], v[24:25], 0, v[40:41]
	global_store_dwordx4 v[40:41], v[8:11], off
	v_bfe_u32 v12, v39, 16, 1
	v_add3_u32 v12, v39, v12, s72
	v_bfe_u32 v8, v13, 16, 1
	v_add3_u32 v8, v13, v8, s72
	v_bfe_u32 v9, v27, 16, 1
	v_lshrrev_b32_e32 v8, 16, v8
	v_add3_u32 v9, v27, v9, s72
	v_and_or_b32 v8, v9, s73, v8
	v_bfe_u32 v9, v29, 16, 1
	v_add3_u32 v9, v29, v9, s72
	v_bfe_u32 v10, v31, 16, 1
	v_lshrrev_b32_e32 v9, 16, v9
	v_add3_u32 v10, v31, v10, s72
	v_and_or_b32 v9, v10, s73, v9
	v_bfe_u32 v10, v33, 16, 1
	v_add3_u32 v10, v33, v10, s72
	v_bfe_u32 v11, v35, 16, 1
	v_lshrrev_b32_e32 v10, 16, v10
	v_add3_u32 v11, v35, v11, s72
	v_and_or_b32 v10, v11, s73, v10
	v_bfe_u32 v11, v37, 16, 1
	v_add3_u32 v11, v37, v11, s72
	v_lshrrev_b32_e32 v11, 16, v11
	v_and_or_b32 v11, v12, s73, v11
	v_or_b32_e32 v12, v5, v16
	v_ashrrev_i32_e32 v13, 31, v12
	v_lshlrev_b64 v[12:13], 12, v[12:13]
	ds_read2_b32 v[26:27], v22 offset0:16 offset1:24
	v_lshl_add_u64 v[12:13], v[24:25], 0, v[12:13]
	global_store_dwordx4 v[12:13], v[8:11], off
	ds_read2_b32 v[12:13], v22 offset0:49 offset1:57
	ds_read2_b32 v[28:29], v22 offset0:82 offset1:90
	ds_read2_b32 v[30:31], v22 offset0:115 offset1:123
	s_waitcnt lgkmcnt(3)
	v_bfe_u32 v8, v26, 16, 1
	v_add3_u32 v8, v26, v8, s72
	s_waitcnt lgkmcnt(2)
	v_bfe_u32 v9, v12, 16, 1
	ds_read2_b32 v[32:33], v22 offset0:148 offset1:156
	v_lshrrev_b32_e32 v8, 16, v8
	v_add3_u32 v9, v12, v9, s72
	ds_read2_b32 v[34:35], v22 offset0:181 offset1:189
	v_and_or_b32 v8, v9, s73, v8
	s_waitcnt lgkmcnt(3)
	v_bfe_u32 v9, v28, 16, 1
	v_add3_u32 v9, v28, v9, s72
	s_waitcnt lgkmcnt(2)
	v_bfe_u32 v10, v30, 16, 1
	ds_read2_b32 v[36:37], v22 offset0:214 offset1:222
	v_lshrrev_b32_e32 v9, 16, v9
	v_add3_u32 v10, v30, v10, s72
	ds_read2_b32 v[38:39], v22 offset0:247 offset1:255
	v_and_or_b32 v9, v10, s73, v9
	s_waitcnt lgkmcnt(3)
	v_bfe_u32 v10, v32, 16, 1
	v_add3_u32 v10, v32, v10, s72
	s_waitcnt lgkmcnt(2)
	v_bfe_u32 v11, v34, 16, 1
	v_lshrrev_b32_e32 v10, 16, v10
	v_add3_u32 v11, v34, v11, s72
	v_and_or_b32 v10, v11, s73, v10
	s_waitcnt lgkmcnt(1)
	v_bfe_u32 v11, v36, 16, 1
	v_or_b32_e32 v40, v5, v17
	v_add3_u32 v11, v36, v11, s72
	s_waitcnt lgkmcnt(0)
	v_bfe_u32 v12, v38, 16, 1
	v_ashrrev_i32_e32 v41, 31, v40
	v_lshrrev_b32_e32 v11, 16, v11
	v_add3_u32 v12, v38, v12, s72
	v_lshlrev_b64 v[40:41], 12, v[40:41]
	v_and_or_b32 v11, v12, s73, v11
	v_lshl_add_u64 v[40:41], v[24:25], 0, v[40:41]
	global_store_dwordx4 v[40:41], v[8:11], off
	v_bfe_u32 v12, v39, 16, 1
	v_add3_u32 v12, v39, v12, s72
	v_bfe_u32 v8, v27, 16, 1
	v_add3_u32 v8, v27, v8, s72
	v_bfe_u32 v9, v13, 16, 1
	v_lshrrev_b32_e32 v8, 16, v8
	v_add3_u32 v9, v13, v9, s72
	v_and_or_b32 v8, v9, s73, v8
	v_bfe_u32 v9, v29, 16, 1
	v_add3_u32 v9, v29, v9, s72
	v_bfe_u32 v10, v31, 16, 1
	v_lshrrev_b32_e32 v9, 16, v9
	v_add3_u32 v10, v31, v10, s72
	v_and_or_b32 v9, v10, s73, v9
	v_bfe_u32 v10, v33, 16, 1
	v_add3_u32 v10, v33, v10, s72
	v_bfe_u32 v11, v35, 16, 1
	v_lshrrev_b32_e32 v10, 16, v10
	v_add3_u32 v11, v35, v11, s72
	v_and_or_b32 v10, v11, s73, v10
	v_bfe_u32 v11, v37, 16, 1
	v_add3_u32 v11, v37, v11, s72
	v_lshrrev_b32_e32 v11, 16, v11
	v_and_or_b32 v11, v12, s73, v11
	v_or_b32_e32 v12, v5, v18
	v_ashrrev_i32_e32 v13, 31, v12
	v_lshlrev_b64 v[12:13], 12, v[12:13]
	v_lshl_add_u64 v[12:13], v[24:25], 0, v[12:13]
	global_store_dwordx4 v[12:13], v[8:11], off
	v_add_u32_e32 v23, s86, v23
	s_movk_i32 s0, 0x15ff
	s_waitcnt lgkmcnt(0)
	v_cmp_lt_i32_e64 s[0:1], s0, v23
	s_or_b64 s[4:5], s[0:1], s[4:5]
	s_andn2_b64 exec, exec, s[4:5]
	s_cbranch_execnz .LBB0_386

; __device__ __forceinline__ void transpose_item(const float* W, int K, int N, bf16* WT, int dst_row0, LAS float* scr, int k0, int n0, int lane) {
; #pragma unroll 8
;     for (int i = 0; i < 32; ++i) { const int kk = 2 * i + (lane >> 5); scr[kk * 33 + (lane & 31)] = W[(size_t)(k0 + kk) * N + n0 + (lane & 31)]; }
;     asm volatile("s_waitcnt vmcnt(0) lgkmcnt(0)" ::: "memory");
.LBB0_392:
	s_lshl_b32 s8, s3, 1
	s_lshl_b32 s7, s2, 1
	v_or_b32_e32 v11, s8, v0
	v_or_b32_e32 v9, s7, v1
	v_add_u32_e32 v22, v11, v10
	v_add_u32_e32 v20, v9, v5
	v_ashrrev_i32_e32 v23, 31, v22
	v_ashrrev_i32_e32 v21, 31, v20
	v_lshlrev_b64 v[22:23], 13, v[22:23]
	v_lshlrev_b64 v[20:21], 13, v[20:21]
	v_lshl_add_u64 v[22:23], v[12:13], 0, v[22:23]
	v_lshl_add_u64 v[20:21], v[12:13], 0, v[20:21]
	global_load_dword v100, v[22:23], off
	global_load_dword v101, v[20:21], off
	v_mad_u64_u32 v[120:121], s[10:11], v11, s55, v[4:5]
	v_mad_u64_u32 v[122:123], s[10:11], v9, s55, v[4:5]
	s_add_i32 s10, s8, 4
	s_add_i32 s9, s7, 4
	v_or_b32_e32 v11, s10, v0
	v_or_b32_e32 v9, s9, v1
	s_add_i32 s9, s7, 8
	s_add_i32 s3, s3, 16
	s_add_i32 s2, s2, 16
	s_add_i32 s6, s6, -16
	v_add_u32_e32 v22, v11, v10
	v_add_u32_e32 v20, v9, v5
	v_ashrrev_i32_e32 v23, 31, v22
	v_ashrrev_i32_e32 v21, 31, v20
	v_lshlrev_b64 v[22:23], 13, v[22:23]
	v_lshlrev_b64 v[20:21], 13, v[20:21]
	v_lshl_add_u64 v[22:23], v[12:13], 0, v[22:23]
	v_lshl_add_u64 v[20:21], v[12:13], 0, v[20:21]
	global_load_dword v102, v[22:23], off
	global_load_dword v103, v[20:21], off
	v_mad_u64_u32 v[124:125], s[10:11], v11, s55, v[4:5]
	v_mad_u64_u32 v[126:127], s[10:11], v9, s55, v[4:5]
	s_add_i32 s10, s8, 8
	s_nop 0
	v_or_b32_e32 v11, s10, v0
	v_or_b32_e32 v9, s9, v1
	s_add_i32 s9, s7, 12
	v_add_u32_e32 v22, v11, v10
	v_add_u32_e32 v20, v9, v5
	v_ashrrev_i32_e32 v23, 31, v22
	v_ashrrev_i32_e32 v21, 31, v20
	v_lshlrev_b64 v[22:23], 13, v[22:23]
	v_lshlrev_b64 v[20:21], 13, v[20:21]
	v_lshl_add_u64 v[22:23], v[12:13], 0, v[22:23]
	v_lshl_add_u64 v[20:21], v[12:13], 0, v[20:21]
	global_load_dword v104, v[22:23], off
	global_load_dword v105, v[20:21], off
	v_mad_u64_u32 v[128:129], s[10:11], v11, s55, v[4:5]
	v_mad_u64_u32 v[130:131], s[10:11], v9, s55, v[4:5]
	s_add_i32 s10, s8, 12
	s_nop 0
	v_or_b32_e32 v11, s10, v0
	v_or_b32_e32 v9, s9, v1
	s_add_i32 s9, s7, 16
	v_add_u32_e32 v22, v11, v10
	v_add_u32_e32 v20, v9, v5
	v_ashrrev_i32_e32 v23, 31, v22
	v_ashrrev_i32_e32 v21, 31, v20
	v_lshlrev_b64 v[22:23], 13, v[22:23]
	v_lshlrev_b64 v[20:21], 13, v[20:21]
	v_lshl_add_u64 v[22:23], v[12:13], 0, v[22:23]
	v_lshl_add_u64 v[20:21], v[12:13], 0, v[20:21]
	global_load_dword v106, v[22:23], off
	global_load_dword v107, v[20:21], off
	v_mad_u64_u32 v[132:133], s[10:11], v11, s55, v[4:5]
	v_mad_u64_u32 v[134:135], s[10:11], v9, s55, v[4:5]
	s_add_i32 s10, s8, 16
	s_nop 0
	v_or_b32_e32 v11, s10, v0
	v_or_b32_e32 v9, s9, v1
	s_add_i32 s9, s7, 20
	v_add_u32_e32 v22, v11, v10
	v_add_u32_e32 v20, v9, v5
	v_ashrrev_i32_e32 v23, 31, v22
	v_ashrrev_i32_e32 v21, 31, v20
	v_lshlrev_b64 v[22:23], 13, v[22:23]
	v_lshlrev_b64 v[20:21], 13, v[20:21]
	v_lshl_add_u64 v[22:23], v[12:13], 0, v[22:23]
	v_lshl_add_u64 v[20:21], v[12:13], 0, v[20:21]
	global_load_dword v108, v[22:23], off
	global_load_dword v109, v[20:21], off
	v_mad_u64_u32 v[136:137], s[10:11], v11, s55, v[4:5]
	v_mad_u64_u32 v[138:139], s[10:11], v9, s55, v[4:5]
	s_add_i32 s10, s8, 20
	s_nop 0
	v_or_b32_e32 v11, s10, v0
	v_or_b32_e32 v9, s9, v1
	s_add_i32 s9, s7, 24
	s_add_i32 s7, s7, 28
	v_add_u32_e32 v22, v11, v10
	v_add_u32_e32 v20, v9, v5
	v_ashrrev_i32_e32 v23, 31, v22
	v_ashrrev_i32_e32 v21, 31, v20
	v_lshlrev_b64 v[22:23], 13, v[22:23]
	v_lshlrev_b64 v[20:21], 13, v[20:21]
	v_lshl_add_u64 v[22:23], v[12:13], 0, v[22:23]
	v_lshl_add_u64 v[20:21], v[12:13], 0, v[20:21]
	global_load_dword v110, v[22:23], off
	global_load_dword v111, v[20:21], off
	v_mad_u64_u32 v[140:141], s[10:11], v11, s55, v[4:5]
	v_mad_u64_u32 v[142:143], s[10:11], v9, s55, v[4:5]
	s_add_i32 s10, s8, 24
	s_nop 0
	v_or_b32_e32 v11, s10, v0
	v_or_b32_e32 v9, s9, v1
	s_add_i32 s8, s8, 28
	s_cmp_lg_u32 s6, 0
	v_add_u32_e32 v22, v11, v10
	v_add_u32_e32 v20, v9, v5
	v_ashrrev_i32_e32 v23, 31, v22
	v_ashrrev_i32_e32 v21, 31, v20
	v_lshlrev_b64 v[22:23], 13, v[22:23]
	v_lshlrev_b64 v[20:21], 13, v[20:21]
	v_lshl_add_u64 v[22:23], v[12:13], 0, v[22:23]
	v_lshl_add_u64 v[20:21], v[12:13], 0, v[20:21]
	global_load_dword v112, v[22:23], off
	global_load_dword v113, v[20:21], off
	v_mad_u64_u32 v[144:145], s[10:11], v11, s55, v[4:5]
	v_mad_u64_u32 v[146:147], s[10:11], v9, s55, v[4:5]
	v_or_b32_e32 v11, s8, v0
	v_or_b32_e32 v9, s7, v1
	v_add_u32_e32 v22, v11, v10
	v_add_u32_e32 v20, v9, v5
	v_ashrrev_i32_e32 v23, 31, v22
	v_ashrrev_i32_e32 v21, 31, v20
	v_lshlrev_b64 v[22:23], 13, v[22:23]
	v_lshlrev_b64 v[20:21], 13, v[20:21]
	v_lshl_add_u64 v[22:23], v[12:13], 0, v[22:23]
	v_lshl_add_u64 v[20:21], v[12:13], 0, v[20:21]
	global_load_dword v114, v[22:23], off
	global_load_dword v115, v[20:21], off
	v_mad_u64_u32 v[148:149], s[8:9], v11, s55, v[4:5]
	v_mad_u64_u32 v[150:151], s[8:9], v9, s55, v[4:5]
	s_waitcnt vmcnt(0)
	ds_write_b32 v120, v100
	ds_write_b32 v122, v101
	ds_write_b32 v124, v102
	ds_write_b32 v126, v103
	ds_write_b32 v128, v104
	ds_write_b32 v130, v105
	ds_write_b32 v132, v106
	ds_write_b32 v134, v107
	ds_write_b32 v136, v108
	ds_write_b32 v138, v109
	ds_write_b32 v140, v110
	ds_write_b32 v142, v111
	ds_write_b32 v144, v112
	ds_write_b32 v146, v113
	ds_write_b32 v148, v114
	ds_write_b32 v150, v115
	s_cbranch_scc1 .LBB0_392
; #define LAS __attribute__((address_space(3)))
; __device__ __forceinline__ unsigned pk2(float lo, float hi) { return f2bf(lo) | (f2bf(hi) << 16); }
; __device__ __forceinline__ void transpose_item(const float* W, int K, int N, bf16* WT, int dst_row0, LAS float* scr, int k0, int n0, int lane) {
;     ...
;     const int c = lane & 7;
; #pragma unroll
;     for (int j = 0; j < 4; ++j) { const int n = (lane >> 3) + 8 * j; const LAS float* s = scr + (8 * c) * 33 + n;
;         u32x4 o; o.x = pk2(s[0 * 33], s[1 * 33]); o.y = pk2(s[2 * 33], s[3 * 33]); o.z = pk2(s[4 * 33], s[5 * 33]); o.w = pk2(s[6 * 33], s[7 * 33]);
;         *(u32x4*)(WT + (size_t)(dst_row0 + n) * K + k0 + 8 * c) = o; }
;     asm volatile("s_waitcnt lgkmcnt(0)" ::: "memory");
; template <int MAP> __device__ __forceinline__ void transpose_matrix(const float* W, int K, int N, bf16* WT, LAS float* scr, int gw, int NGW, int lane) {
;     ...
;     for (int it = gw; it < nitems; it += NGW) {
;         const int kb = it / nblk, nb = it % nblk, n0 = nb * 32; int d = n0;
;         if (MAP == 1) d = n0 < 1024 ? n0 + 2048 : (n0 < 3072 ? n0 - 1024 : n0);
;         if (MAP == 2) d = 256 * (n0 >> 7) + (n0 & 127);
;         if (MAP == 3) d = 256 * (n0 >> 7) + 128 + (n0 & 127);
;         transpose_item(W, K, N, WT, d, scr, kb * 64, n0, lane);
	s_waitcnt vmcnt(0) lgkmcnt(0)
	ds_read2_b32 v[20:21], v19 offset1:8
	ds_read2_b32 v[24:25], v19 offset0:33 offset1:41
	ds_read2_b32 v[26:27], v19 offset0:66 offset1:74
	ds_read2_b32 v[28:29], v19 offset0:99 offset1:107
	ds_read2_b32 v[30:31], v19 offset0:132 offset1:140
	v_ashrrev_i32_e32 v11, 31, v10
	s_waitcnt lgkmcnt(4)
	v_bfe_u32 v5, v20, 16, 1
	v_add3_u32 v5, v20, v5, s72
	s_waitcnt lgkmcnt(3)
	v_bfe_u32 v9, v24, 16, 1
	v_lshrrev_b32_e32 v5, 16, v5
	v_add3_u32 v9, v24, v9, s72
	ds_read2_b32 v[32:33], v19 offset0:165 offset1:173
	v_lshl_add_u64 v[22:23], v[10:11], 1, v[6:7]
	v_and_or_b32 v10, v9, s73, v5
	s_waitcnt lgkmcnt(3)
	v_bfe_u32 v5, v26, 16, 1
	v_add3_u32 v5, v26, v5, s72
	s_waitcnt lgkmcnt(2)
	v_bfe_u32 v9, v28, 16, 1
	ds_read2_b32 v[34:35], v19 offset0:198 offset1:206
	v_lshrrev_b32_e32 v5, 16, v5
	v_add3_u32 v9, v28, v9, s72
	ds_read2_b32 v[36:37], v19 offset0:231 offset1:239
	v_and_or_b32 v11, v9, s73, v5
	s_waitcnt lgkmcnt(3)
	v_bfe_u32 v5, v30, 16, 1
	v_add3_u32 v5, v30, v5, s72
	s_waitcnt lgkmcnt(2)
	v_bfe_u32 v9, v32, 16, 1
	v_lshrrev_b32_e32 v5, 16, v5
	v_add3_u32 v9, v32, v9, s72
	v_and_or_b32 v12, v9, s73, v5
	s_waitcnt lgkmcnt(1)
	v_bfe_u32 v5, v34, 16, 1
	v_add3_u32 v5, v34, v5, s72
	s_waitcnt lgkmcnt(0)
	v_bfe_u32 v9, v36, 16, 1
	v_lshrrev_b32_e32 v5, 16, v5
	v_add3_u32 v9, v36, v9, s72
	v_and_or_b32 v13, v9, s73, v5
	v_or_b32_e32 v5, v8, v15
	s_movk_i32 s2, 0x1600
	v_mul_lo_u32 v38, v5, s2
	v_bfe_u32 v5, v21, 16, 1
	v_ashrrev_i32_e32 v39, 31, v38
	v_add3_u32 v5, v21, v5, s72
	v_bfe_u32 v9, v25, 16, 1
	v_lshl_add_u64 v[38:39], v[38:39], 1, v[22:23]
	v_lshrrev_b32_e32 v5, 16, v5
	v_add3_u32 v9, v25, v9, s72
	global_store_dwordx4 v[38:39], v[10:13], off
	ds_read2_b32 v[24:25], v19 offset0:16 offset1:24
	v_add_u32_e32 v14, s86, v14
	v_and_or_b32 v10, v9, s73, v5
	v_bfe_u32 v5, v27, 16, 1
	v_add3_u32 v5, v27, v5, s72
	v_bfe_u32 v9, v29, 16, 1
	v_lshrrev_b32_e32 v5, 16, v5
	v_add3_u32 v9, v29, v9, s72
	v_and_or_b32 v11, v9, s73, v5
	v_bfe_u32 v5, v31, 16, 1
	v_add3_u32 v5, v31, v5, s72
	v_bfe_u32 v9, v33, 16, 1
	v_lshrrev_b32_e32 v5, 16, v5
	v_add3_u32 v9, v33, v9, s72
	v_and_or_b32 v12, v9, s73, v5
	v_bfe_u32 v5, v35, 16, 1
	v_add3_u32 v5, v35, v5, s72
	v_bfe_u32 v9, v37, 16, 1
	v_lshrrev_b32_e32 v5, 16, v5
	v_add3_u32 v9, v37, v9, s72
	v_and_or_b32 v13, v9, s73, v5
	v_or_b32_e32 v5, v8, v16
	v_mul_lo_u32 v20, v5, s2
	v_ashrrev_i32_e32 v21, 31, v20
	v_lshl_add_u64 v[20:21], v[20:21], 1, v[22:23]
	global_store_dwordx4 v[20:21], v[10:13], off
	ds_read2_b32 v[20:21], v19 offset0:49 offset1:57
	ds_read2_b32 v[26:27], v19 offset0:82 offset1:90
	ds_read2_b32 v[28:29], v19 offset0:115 offset1:123
	s_waitcnt lgkmcnt(3)
	v_bfe_u32 v5, v24, 16, 1
	v_add3_u32 v5, v24, v5, s72
	s_waitcnt lgkmcnt(2)
	v_bfe_u32 v9, v20, 16, 1
	ds_read2_b32 v[30:31], v19 offset0:148 offset1:156
	v_lshrrev_b32_e32 v5, 16, v5
	v_add3_u32 v9, v20, v9, s72
	ds_read2_b32 v[32:33], v19 offset0:181 offset1:189
	v_and_or_b32 v10, v9, s73, v5
	s_waitcnt lgkmcnt(3)
	v_bfe_u32 v5, v26, 16, 1
	v_add3_u32 v5, v26, v5, s72
	s_waitcnt lgkmcnt(2)
	v_bfe_u32 v9, v28, 16, 1
	ds_read2_b32 v[34:35], v19 offset0:214 offset1:222
	v_lshrrev_b32_e32 v5, 16, v5
	v_add3_u32 v9, v28, v9, s72
	ds_read2_b32 v[36:37], v19 offset0:247 offset1:255
	v_and_or_b32 v11, v9, s73, v5
	s_waitcnt lgkmcnt(3)
	v_bfe_u32 v5, v30, 16, 1
	v_add3_u32 v5, v30, v5, s72
	s_waitcnt lgkmcnt(2)
	v_bfe_u32 v9, v32, 16, 1
	v_lshrrev_b32_e32 v5, 16, v5
	v_add3_u32 v9, v32, v9, s72
	v_and_or_b32 v12, v9, s73, v5
	s_waitcnt lgkmcnt(1)
	v_bfe_u32 v5, v34, 16, 1
	v_add3_u32 v5, v34, v5, s72
	s_waitcnt lgkmcnt(0)
	v_bfe_u32 v9, v36, 16, 1
	v_lshrrev_b32_e32 v5, 16, v5
	v_add3_u32 v9, v36, v9, s72
	v_and_or_b32 v13, v9, s73, v5
	v_or_b32_e32 v5, v8, v17
	v_mul_lo_u32 v38, v5, s2
	v_bfe_u32 v5, v25, 16, 1
	v_ashrrev_i32_e32 v39, 31, v38
	v_add3_u32 v5, v25, v5, s72
	v_bfe_u32 v9, v21, 16, 1
	v_lshl_add_u64 v[38:39], v[38:39], 1, v[22:23]
	v_lshrrev_b32_e32 v5, 16, v5
	v_add3_u32 v9, v21, v9, s72
	global_store_dwordx4 v[38:39], v[10:13], off
	s_nop 1
	v_and_or_b32 v10, v9, s73, v5
	v_bfe_u32 v5, v27, 16, 1
	v_add3_u32 v5, v27, v5, s72
	v_bfe_u32 v9, v29, 16, 1
	v_lshrrev_b32_e32 v5, 16, v5
	v_add3_u32 v9, v29, v9, s72
	v_and_or_b32 v11, v9, s73, v5
	v_bfe_u32 v5, v31, 16, 1
	v_add3_u32 v5, v31, v5, s72
	v_bfe_u32 v9, v33, 16, 1
	v_lshrrev_b32_e32 v5, 16, v5
	v_add3_u32 v9, v33, v9, s72
	v_and_or_b32 v12, v9, s73, v5
	v_bfe_u32 v5, v35, 16, 1
	v_add3_u32 v5, v35, v5, s72
	v_bfe_u32 v9, v37, 16, 1
	v_lshrrev_b32_e32 v5, 16, v5
	v_add3_u32 v9, v37, v9, s72
	v_and_or_b32 v13, v9, s73, v5
	v_or_b32_e32 v5, v8, v18
	v_mul_lo_u32 v8, v5, s2
	v_ashrrev_i32_e32 v9, 31, v8
	v_lshl_add_u64 v[8:9], v[8:9], 1, v[22:23]
	global_store_dwordx4 v[8:9], v[10:13], off
	s_movk_i32 s2, 0x15ff
	s_waitcnt lgkmcnt(0)
	v_cmp_lt_i32_e32 vcc, s2, v14
	s_or_b64 s[4:5], vcc, s[4:5]
	s_andn2_b64 exec, exec, s[4:5]
	s_cbranch_execnz .LBB0_391
